# rms row loops visit rows in serpentine order (most recently written first)
# speedup vs baseline: 1.0109x; 1.0002x over previous
; template <bool TO_BF16>
; DI void rms_rows(const int tid, const float* src, const float* gam, bf16_t* dst, float* fdst, int G, int c) {
;     constexpr int NR = 8;
;     const int wave = tid >> 6, lane = tid & 63;
;     f32x4 g4[4];
; #pragma unroll
;     for (int k = 0; k < 4; ++k) g4[k] = *(const f32x4*)(gam + k * 256 + lane * 4);
;     for (int r = (c * 8 + wave) * NR; r < MTOK; r += G * 8 * NR) {
;         f32x4 v[NR][4]; float s[NR];
; #pragma unroll
;         for (int q = 0; q < NR; ++q)
; #pragma unroll
;             for (int k = 0; k < 4; ++k) v[q][k] = *(const f32x4*)(src + (size_t)(r + q) * 1024 + k * 256 + lane * 4);
.LBB0_67:
	s_cmpk_gt_i32 s64, 0x63
	s_mov_b64 s[4:5], -1
	s_cbranch_scc0 .LBB0_72
	v_ashrrev_i32_e32 v0, 3, v182
	v_and_b32_e32 v0, -8, v0
	v_readlane_b32 s4, v250, 0
	s_nop 1
	v_add_u32_e32 v144, s4, v0
	s_mov_b32 s4, 0x10000
	v_cmp_gt_i32_e32 vcc, s4, v144
	s_and_saveexec_b64 s[4:5], vcc
	v_readlane_b32 s16, v253, 10
	v_readlane_b32 s17, v253, 11
	s_movk_i32 s18, 0xd000
	s_movk_i32 s24, 0xe000
	s_movk_i32 s25, 0xf000
	s_mov_b32 s26, 0x358637bd
	s_cbranch_execz .LBB0_71
	s_and_b64 s[0:1], s[0:1], exec
	s_cselect_b32 s0, 0x1000, 0
	s_add_u32 s0, s48, s0
	v_lshlrev_b32_e32 v0, 4, v182
	s_addc_u32 s1, s49, 0
	v_and_b32_e32 v12, 0x3f0, v0
	global_load_dwordx4 v[0:3], v12, s[0:1] offset:3072
	global_load_dwordx4 v[4:7], v12, s[0:1] offset:2048
	global_load_dwordx4 v[8:11], v12, s[0:1] offset:1024
	s_nop 0
	global_load_dwordx4 v[12:15], v12, s[0:1]
	v_and_b32_e32 v16, 64, v234
	v_add_u32_e32 v16, 64, v16
	v_xor_b32_e32 v17, 32, v234
	v_cmp_lt_i32_e32 vcc, v17, v16
	v_ashrrev_i32_e32 v145, 31, v144
	v_and_b32_e32 v18, 63, v182
	v_cndmask_b32_e32 v17, v234, v17, vcc
	v_lshlrev_b32_e32 v178, 2, v17
	v_xor_b32_e32 v17, 16, v234
	v_cmp_lt_i32_e32 vcc, v17, v16
	v_readlane_b32 s0, v253, 8
	v_readlane_b32 s1, v253, 9
	v_cndmask_b32_e32 v17, v234, v17, vcc
	v_lshlrev_b32_e32 v179, 2, v17
	v_xor_b32_e32 v17, 8, v234
	v_cmp_lt_i32_e32 vcc, v17, v16
	s_mov_b64 s[14:15], 0
	s_nop 0
	v_cndmask_b32_e32 v17, v234, v17, vcc
	v_lshlrev_b32_e32 v180, 2, v17
	v_xor_b32_e32 v17, 4, v234
	v_cmp_lt_i32_e32 vcc, v17, v16
	s_nop 1
	v_cndmask_b32_e32 v17, v234, v17, vcc
	v_lshlrev_b32_e32 v183, 2, v17
	v_xor_b32_e32 v17, 2, v234
	v_cmp_lt_i32_e32 vcc, v17, v16
	s_nop 1
	v_cndmask_b32_e32 v17, v234, v17, vcc
	v_lshlrev_b32_e32 v184, 2, v17
	v_xor_b32_e32 v17, 1, v234
	v_cmp_lt_i32_e32 vcc, v17, v16
	s_nop 1
	v_cndmask_b32_e32 v16, v234, v17, vcc
	v_lshlrev_b32_e32 v185, 2, v16
	v_lshlrev_b64 v[16:17], 11, v[144:145]
	v_lshl_or_b32 v16, v18, 3, v16
	v_lshl_add_u64 v[146:147], s[0:1], 0, v[16:17]
	v_lshlrev_b64 v[16:17], 12, v[144:145]
	v_readlane_b32 s0, v253, 4
	v_lshl_or_b32 v16, v18, 4, v16
	v_readlane_b32 s1, v253, 5
	s_nop 1
	v_lshl_add_u64 v[148:149], s[0:1], 0, v[16:17]
	v_readlane_b32 s98, v253, 4
	v_readlane_b32 s99, v253, 5
	v_readlane_b32 s100, v253, 8
	v_readlane_b32 s101, v253, 9
	s_nop 3
	v_bfe_u32 v148, v144, 11, 3
	v_lshrrev_b32_e32 v149, 14, v144
	v_sub_u32_e32 v149, 3, v149
	v_lshlrev_b32_e32 v149, 11, v149
	v_lshl_or_b32 v148, v148, 13, v149
	v_and_b32_e32 v149, 0x7ff, v144
	v_or_b32_e32 v148, v148, v149
	v_lshlrev_b32_e32 v148, 12, v148
	v_and_b32_e32 v149, 63, v182
	v_lshl_or_b32 v148, v149, 4, v148
	v_mov_b32_e32 v149, 0
	v_lshl_add_u64 v[148:149], s[98:99], 0, v[148:149]
	v_bfe_u32 v146, v144, 11, 3
	v_lshrrev_b32_e32 v147, 14, v144
	v_sub_u32_e32 v147, 3, v147
	v_lshlrev_b32_e32 v147, 11, v147
	v_lshl_or_b32 v146, v146, 13, v147
	v_and_b32_e32 v147, 0x7ff, v144
	v_or_b32_e32 v146, v146, v147
	v_lshlrev_b32_e32 v146, 11, v146
	v_and_b32_e32 v147, 63, v182
	v_lshl_or_b32 v146, v147, 3, v146
	v_mov_b32_e32 v147, 0
	v_lshl_add_u64 v[146:147], s[100:101], 0, v[146:147]
.LBB0_70:
	v_add_co_u32_e32 v16, vcc, 0xffff9000, v148
	v_add_u32_e32 v144, s66, v144
	s_nop 0
	v_addc_co_u32_e32 v17, vcc, -1, v149, vcc
	global_load_dwordx4 v[140:143], v[16:17], off offset:-3072
	global_load_dwordx4 v[136:139], v[16:17], off offset:-2048
	global_load_dwordx4 v[132:135], v[16:17], off offset:-1024
	global_load_dwordx4 v[128:131], v[16:17], off
	v_add_co_u32_e32 v16, vcc, 0xffffa000, v148
	s_waitcnt vmcnt(0)
	v_mov_b32_e32 v152, v141
	v_addc_co_u32_e32 v17, vcc, -1, v149, vcc
	global_load_dwordx4 v[124:127], v[16:17], off offset:-3072
	global_load_dwordx4 v[120:123], v[16:17], off offset:-2048
	global_load_dwordx4 v[116:119], v[16:17], off offset:-1024
	global_load_dwordx4 v[112:115], v[16:17], off
	v_add_co_u32_e32 v16, vcc, 0xffffb000, v148
	s_waitcnt vmcnt(6)
	v_mov_b32_e32 v153, v137
	v_addc_co_u32_e32 v17, vcc, -1, v149, vcc
	global_load_dwordx4 v[108:111], v[16:17], off offset:-3072
	global_load_dwordx4 v[104:107], v[16:17], off offset:-2048
	global_load_dwordx4 v[100:103], v[16:17], off offset:-1024
	global_load_dwordx4 v[96:99], v[16:17], off
	v_add_co_u32_e32 v16, vcc, 0xffffc000, v148
	v_mov_b32_e32 v150, v140
	s_nop 0
	v_addc_co_u32_e32 v17, vcc, -1, v149, vcc
	global_load_dwordx4 v[92:95], v[16:17], off offset:-3072
	global_load_dwordx4 v[88:91], v[16:17], off offset:-2048
	global_load_dwordx4 v[84:87], v[16:17], off offset:-1024
	global_load_dwordx4 v[80:83], v[16:17], off
	v_add_co_u32_e32 v16, vcc, 0xffffd000, v148
	v_mov_b32_e32 v151, v136
	s_nop 0
	v_addc_co_u32_e32 v17, vcc, -1, v149, vcc
	global_load_dwordx4 v[76:79], v[16:17], off offset:-3072
	global_load_dwordx4 v[56:59], v[16:17], off offset:-2048
	global_load_dwordx4 v[52:55], v[16:17], off offset:-1024
	global_load_dwordx4 v[48:51], v[16:17], off
	v_add_co_u32_e32 v16, vcc, 0xffffe000, v148
	v_pk_mul_f32 v[152:153], v[152:153], v[152:153]
	s_nop 0
	v_addc_co_u32_e32 v17, vcc, -1, v149, vcc
	global_load_dwordx4 v[44:47], v[16:17], off offset:-3072
	global_load_dwordx4 v[40:43], v[16:17], off offset:-2048
	global_load_dwordx4 v[36:39], v[16:17], off offset:-1024
	global_load_dwordx4 v[32:35], v[16:17], off
	v_add_co_u32_e32 v16, vcc, 0xfffff000, v148
	v_pk_fma_f32 v[150:151], v[150:151], v[150:151], v[152:153]
	s_nop 0
	v_addc_co_u32_e32 v17, vcc, -1, v149, vcc
	global_load_dwordx4 v[28:31], v[16:17], off offset:-3072
	global_load_dwordx4 v[24:27], v[16:17], off offset:-2048
	global_load_dwordx4 v[20:23], v[16:17], off offset:-1024
	s_nop 0
	global_load_dwordx4 v[16:19], v[148:149], off offset:-4096
	global_load_dwordx4 v[72:75], v[148:149], off offset:-3072
	global_load_dwordx4 v[68:71], v[148:149], off offset:-2048
	global_load_dwordx4 v[64:67], v[148:149], off offset:-1024
	global_load_dwordx4 v[60:63], v[148:149], off
	v_mov_b32_e32 v152, v142
	v_mov_b32_e32 v153, v138
	v_pk_fma_f32 v[150:151], v[152:153], v[152:153], v[150:151]
	v_mov_b32_e32 v152, v143
	v_mov_b32_e32 v153, v139
	v_pk_fma_f32 v[174:175], v[152:153], v[152:153], v[150:151]
	s_waitcnt vmcnt(29)
; template <bool TO_BF16>
; DI void rms_rows(const int tid, const float* src, const float* gam, bf16_t* dst, float* fdst, int G, int c) {
;     ...
;     for (int r = (c * 8 + wave) * NR; r < MTOK; r += G * 8 * NR) {
;         f32x4 v[NR][4]; float s[NR];
; #pragma unroll
;         for (int q = 0; q < NR; ++q)
; #pragma unroll
;             for (int k = 0; k < 4; ++k) v[q][k] = *(const f32x4*)(src + (size_t)(r + q) * 1024 + k * 256 + lane * 4);
; #pragma unroll
;         for (int q = 0; q < NR; ++q) { s[q] = 0.f;
; #pragma unroll
;             for (int k = 0; k < 4; ++k) s[q] += v[q][k][0] * v[q][k][0] + v[q][k][1] * v[q][k][1] + v[q][k][2] * v[q][k][2] + v[q][k][3] * v[q][k][3]; }
	v_mov_b32_e32 v152, v133
	s_waitcnt vmcnt(28)
	v_mov_b32_e32 v153, v129
	v_mov_b32_e32 v150, v132
	v_mov_b32_e32 v151, v128
	v_pk_mul_f32 v[152:153], v[152:153], v[152:153]
	v_bfe_u32 v148, v144, 11, 3
	v_lshrrev_b32_e32 v149, 14, v144
	v_sub_u32_e32 v149, 3, v149
	v_lshlrev_b32_e32 v149, 11, v149
	v_lshl_or_b32 v148, v148, 13, v149
	v_and_b32_e32 v149, 0x7ff, v144
	v_or_b32_e32 v148, v148, v149
	v_lshlrev_b32_e32 v148, 12, v148
	v_and_b32_e32 v149, 63, v182
	v_lshl_or_b32 v148, v149, 4, v148
	v_mov_b32_e32 v149, 0
	v_lshl_add_u64 v[148:149], s[98:99], 0, v[148:149]
	v_pk_fma_f32 v[150:151], v[150:151], v[150:151], v[152:153]
	v_mov_b32_e32 v152, v134
	v_mov_b32_e32 v153, v130
	v_pk_fma_f32 v[150:151], v[152:153], v[152:153], v[150:151]
	v_mov_b32_e32 v152, v135
	v_mov_b32_e32 v153, v131
	v_pk_fma_f32 v[176:177], v[152:153], v[152:153], v[150:151]
	s_waitcnt vmcnt(0)
	v_mov_b32_e32 v152, v125
	s_waitcnt vmcnt(26)
	v_mov_b32_e32 v153, v121
	v_mov_b32_e32 v150, v124
	v_mov_b32_e32 v151, v120
	v_pk_mul_f32 v[152:153], v[152:153], v[152:153]
	s_waitcnt vmcnt(5)
	v_mov_b32_e32 v154, v21
	v_pk_fma_f32 v[150:151], v[150:151], v[150:151], v[152:153]
	v_mov_b32_e32 v152, v126
	v_mov_b32_e32 v153, v122
	v_pk_fma_f32 v[150:151], v[152:153], v[152:153], v[150:151]
	v_mov_b32_e32 v152, v127
	v_mov_b32_e32 v153, v123
	v_pk_fma_f32 v[186:187], v[152:153], v[152:153], v[150:151]
	v_mov_b32_e32 v152, v117
	v_mov_b32_e32 v153, v113
	v_mov_b32_e32 v150, v116
	v_mov_b32_e32 v151, v112
	v_pk_mul_f32 v[152:153], v[152:153], v[152:153]
	s_waitcnt vmcnt(4)
	v_mov_b32_e32 v155, v17
	v_pk_fma_f32 v[150:151], v[150:151], v[150:151], v[152:153]
	v_mov_b32_e32 v152, v118
	v_mov_b32_e32 v153, v114
	v_pk_fma_f32 v[150:151], v[152:153], v[152:153], v[150:151]
	v_mov_b32_e32 v152, v119
	v_mov_b32_e32 v153, v115
	v_pk_fma_f32 v[188:189], v[152:153], v[152:153], v[150:151]
	v_mov_b32_e32 v152, v109
	v_mov_b32_e32 v153, v105
	v_mov_b32_e32 v150, v108
	v_mov_b32_e32 v151, v104
	v_pk_mul_f32 v[152:153], v[152:153], v[152:153]
	v_pk_mul_f32 v[154:155], v[154:155], v[154:155]
	v_pk_fma_f32 v[150:151], v[150:151], v[150:151], v[152:153]
	v_mov_b32_e32 v152, v110
	v_mov_b32_e32 v153, v106
	v_pk_fma_f32 v[150:151], v[152:153], v[152:153], v[150:151]
	v_mov_b32_e32 v152, v111
	v_mov_b32_e32 v153, v107
	v_pk_fma_f32 v[166:167], v[152:153], v[152:153], v[150:151]
	v_mov_b32_e32 v152, v101
	v_mov_b32_e32 v153, v97
	v_mov_b32_e32 v150, v100
	v_mov_b32_e32 v151, v96
	v_pk_mul_f32 v[152:153], v[152:153], v[152:153]
	s_waitcnt vmcnt(3)
	v_mov_b32_e32 v156, v73
	v_pk_fma_f32 v[150:151], v[150:151], v[150:151], v[152:153]
	v_mov_b32_e32 v152, v102
	v_mov_b32_e32 v153, v98
	v_pk_fma_f32 v[150:151], v[152:153], v[152:153], v[150:151]
	v_mov_b32_e32 v152, v103
	v_mov_b32_e32 v153, v99
	v_pk_fma_f32 v[168:169], v[152:153], v[152:153], v[150:151]
	v_mov_b32_e32 v152, v93
	v_mov_b32_e32 v153, v89
	v_mov_b32_e32 v150, v92
	v_mov_b32_e32 v151, v88
	v_pk_mul_f32 v[152:153], v[152:153], v[152:153]
	s_waitcnt vmcnt(2)
	v_mov_b32_e32 v157, v69
	v_pk_fma_f32 v[150:151], v[150:151], v[150:151], v[152:153]
	v_mov_b32_e32 v152, v94
	v_mov_b32_e32 v153, v90
	v_pk_fma_f32 v[150:151], v[152:153], v[152:153], v[150:151]
	v_mov_b32_e32 v152, v95
	v_mov_b32_e32 v153, v91
	v_pk_fma_f32 v[170:171], v[152:153], v[152:153], v[150:151]
	v_mov_b32_e32 v152, v85
	v_mov_b32_e32 v153, v81
	v_mov_b32_e32 v150, v84
	v_mov_b32_e32 v151, v80
	v_pk_mul_f32 v[152:153], v[152:153], v[152:153]
	v_pk_mul_f32 v[156:157], v[156:157], v[156:157]
	v_pk_fma_f32 v[150:151], v[150:151], v[150:151], v[152:153]
	v_mov_b32_e32 v152, v86
	v_mov_b32_e32 v153, v82
	v_pk_fma_f32 v[150:151], v[152:153], v[152:153], v[150:151]
	v_mov_b32_e32 v152, v87
	v_mov_b32_e32 v153, v83
	v_pk_fma_f32 v[172:173], v[152:153], v[152:153], v[150:151]
	v_mov_b32_e32 v152, v77
	v_mov_b32_e32 v153, v57
	v_mov_b32_e32 v150, v76
	v_mov_b32_e32 v151, v56
	v_pk_mul_f32 v[152:153], v[152:153], v[152:153]
	s_waitcnt vmcnt(1)
	v_mov_b32_e32 v190, v65
	v_pk_fma_f32 v[150:151], v[150:151], v[150:151], v[152:153]
	v_mov_b32_e32 v152, v78
	v_mov_b32_e32 v153, v58
	v_pk_fma_f32 v[150:151], v[152:153], v[152:153], v[150:151]
	v_mov_b32_e32 v152, v79
	v_mov_b32_e32 v153, v59
	v_pk_fma_f32 v[158:159], v[152:153], v[152:153], v[150:151]
	v_mov_b32_e32 v152, v53
	v_mov_b32_e32 v153, v49
	v_mov_b32_e32 v150, v52
	v_mov_b32_e32 v151, v48
	v_pk_mul_f32 v[152:153], v[152:153], v[152:153]
	s_waitcnt vmcnt(0)
; template <bool TO_BF16>
; DI void rms_rows(const int tid, const float* src, const float* gam, bf16_t* dst, float* fdst, int G, int c) {
;     ...
;         for (int q = 0; q < NR; ++q) { s[q] = 0.f;
; #pragma unroll
;             for (int k = 0; k < 4; ++k) s[q] += v[q][k][0] * v[q][k][0] + v[q][k][1] * v[q][k][1] + v[q][k][2] * v[q][k][2] + v[q][k][3] * v[q][k][3]; }
; #pragma unroll
;         for (int o = 32; o > 0; o >>= 1)
; #pragma unroll
;             for (int q = 0; q < NR; ++q) s[q] += __shfl_xor(s[q], o);
; #pragma unroll
;         for (int q = 0; q < NR; ++q) { const float sc = rsqrtf(s[q] * (1.f / 1024.f) + 1e-6f);
; #pragma unroll
;             for (int k = 0; k < 4; ++k) {
;                 if (TO_BF16) { u32x2 o; o.x = pk2(v[q][k][0] * sc * g4[k][0], v[q][k][1] * sc * g4[k][1]); o.y = pk2(v[q][k][2] * sc * g4[k][2], v[q][k][3] * sc * g4[k][3]);
;                     *(u32x2*)(dst + (size_t)(r + q) * 1024 + k * 256 + lane * 4) = o; }
;                 else *(f32x4*)(fdst + (size_t)(r + q) * 1024 + k * 256 + lane * 4) = v[q][k] * sc * g4[k]; } }
	v_mov_b32_e32 v191, v61
	v_pk_fma_f32 v[150:151], v[150:151], v[150:151], v[152:153]
	v_mov_b32_e32 v152, v54
	v_mov_b32_e32 v153, v50
	v_pk_fma_f32 v[150:151], v[152:153], v[152:153], v[150:151]
	v_mov_b32_e32 v152, v55
	v_mov_b32_e32 v153, v51
	v_pk_fma_f32 v[160:161], v[152:153], v[152:153], v[150:151]
	v_mov_b32_e32 v152, v45
	v_mov_b32_e32 v153, v41
	v_mov_b32_e32 v150, v44
	v_mov_b32_e32 v151, v40
	v_pk_mul_f32 v[152:153], v[152:153], v[152:153]
	v_pk_mul_f32 v[190:191], v[190:191], v[190:191]
	v_pk_fma_f32 v[150:151], v[150:151], v[150:151], v[152:153]
	v_mov_b32_e32 v152, v46
	v_mov_b32_e32 v153, v42
	v_pk_fma_f32 v[150:151], v[152:153], v[152:153], v[150:151]
	v_mov_b32_e32 v152, v47
	v_mov_b32_e32 v153, v43
	v_pk_fma_f32 v[162:163], v[152:153], v[152:153], v[150:151]
	v_mov_b32_e32 v152, v37
	v_mov_b32_e32 v153, v33
	v_mov_b32_e32 v150, v36
	v_mov_b32_e32 v151, v32
	v_pk_mul_f32 v[152:153], v[152:153], v[152:153]
	s_nop 0
	v_pk_fma_f32 v[150:151], v[150:151], v[150:151], v[152:153]
	v_mov_b32_e32 v152, v38
	v_mov_b32_e32 v153, v34
	v_pk_fma_f32 v[150:151], v[152:153], v[152:153], v[150:151]
	v_mov_b32_e32 v152, v39
	v_mov_b32_e32 v153, v35
	v_pk_fma_f32 v[164:165], v[152:153], v[152:153], v[150:151]
	v_mov_b32_e32 v152, v29
	v_mov_b32_e32 v153, v25
	v_mov_b32_e32 v150, v28
	v_mov_b32_e32 v151, v24
	v_pk_mul_f32 v[152:153], v[152:153], v[152:153]
	s_nop 0
	v_pk_fma_f32 v[150:151], v[150:151], v[150:151], v[152:153]
	v_mov_b32_e32 v152, v30
	v_mov_b32_e32 v153, v26
	v_pk_fma_f32 v[150:151], v[152:153], v[152:153], v[150:151]
	v_mov_b32_e32 v152, v31
	v_mov_b32_e32 v153, v27
	v_pk_fma_f32 v[150:151], v[152:153], v[152:153], v[150:151]
	v_mov_b32_e32 v152, v20
	v_mov_b32_e32 v153, v16
	v_pk_fma_f32 v[152:153], v[152:153], v[152:153], v[154:155]
	v_mov_b32_e32 v154, v22
	v_mov_b32_e32 v155, v18
	v_pk_fma_f32 v[152:153], v[154:155], v[154:155], v[152:153]
	v_mov_b32_e32 v154, v23
	v_mov_b32_e32 v155, v19
	v_pk_fma_f32 v[152:153], v[154:155], v[154:155], v[152:153]
	v_mov_b32_e32 v154, v72
	v_mov_b32_e32 v155, v68
	v_pk_fma_f32 v[154:155], v[154:155], v[154:155], v[156:157]
	v_mov_b32_e32 v156, v74
	v_mov_b32_e32 v157, v70
	v_pk_fma_f32 v[154:155], v[156:157], v[156:157], v[154:155]
	v_mov_b32_e32 v156, v75
	v_mov_b32_e32 v157, v71
	v_pk_fma_f32 v[154:155], v[156:157], v[156:157], v[154:155]
	v_mov_b32_e32 v156, v64
	v_mov_b32_e32 v157, v60
	v_pk_fma_f32 v[156:157], v[156:157], v[156:157], v[190:191]
	v_mov_b32_e32 v190, v66
	v_mov_b32_e32 v191, v62
	v_pk_fma_f32 v[156:157], v[190:191], v[190:191], v[156:157]
	v_mov_b32_e32 v190, v67
	v_mov_b32_e32 v191, v63
	v_pk_fma_f32 v[156:157], v[190:191], v[190:191], v[156:157]
	v_mov_b32_e32 v190, v186
	v_mov_b32_e32 v191, v174
	v_mov_b32_e32 v174, v187
	v_pk_add_f32 v[174:175], v[190:191], v[174:175]
	v_mov_b32_e32 v186, v188
	v_mov_b32_e32 v187, v176
	v_pk_add_f32 v[174:175], v[174:175], v[186:187]
	v_mov_b32_e32 v176, v189
	v_pk_add_f32 v[174:175], v[174:175], v[176:177]
	ds_bpermute_b32 v177, v178, v175
	ds_bpermute_b32 v176, v178, v174
	s_waitcnt lgkmcnt(0)
	v_pk_add_f32 v[174:175], v[174:175], v[176:177]
	ds_bpermute_b32 v177, v179, v175
	ds_bpermute_b32 v176, v179, v174
	s_waitcnt lgkmcnt(0)
	v_pk_add_f32 v[174:175], v[174:175], v[176:177]
	ds_bpermute_b32 v177, v180, v175
	ds_bpermute_b32 v176, v180, v174
	s_waitcnt lgkmcnt(0)
	v_pk_add_f32 v[174:175], v[174:175], v[176:177]
	ds_bpermute_b32 v177, v183, v175
	ds_bpermute_b32 v176, v183, v174
	s_waitcnt lgkmcnt(0)
	v_pk_add_f32 v[174:175], v[174:175], v[176:177]
	ds_bpermute_b32 v177, v184, v175
	ds_bpermute_b32 v176, v184, v174
	s_waitcnt lgkmcnt(0)
	v_pk_add_f32 v[174:175], v[174:175], v[176:177]
	ds_bpermute_b32 v177, v185, v175
	ds_bpermute_b32 v176, v185, v174
	s_waitcnt lgkmcnt(0)
	v_pk_add_f32 v[176:177], v[174:175], v[176:177]
	v_mov_b64_e32 v[174:175], s[26:27]
	v_pk_fma_f32 v[176:177], v[176:177], s[2:3], v[174:175] op_sel_hi:[1,0,0]
	s_nop 0
	v_mul_f32_e32 v145, 0x4b800000, v177
	v_cmp_gt_f32_e64 s[0:1], s3, v177
	v_cmp_gt_f32_e32 vcc, s3, v176
	s_nop 0
	v_cndmask_b32_e64 v145, v177, v145, s[0:1]
	v_rsq_f32_e32 v145, v145
	s_nop 0
	v_mul_f32_e32 v177, 0x45800000, v145
	v_cndmask_b32_e64 v186, v145, v177, s[0:1]
	v_pk_mul_f32 v[140:141], v[140:141], v[186:187] op_sel_hi:[1,0]
	v_pk_mul_f32 v[142:143], v[142:143], v[186:187] op_sel_hi:[1,0]
	v_pk_mul_f32 v[140:141], v[12:13], v[140:141]
	v_pk_mul_f32 v[142:143], v[14:15], v[142:143]
	v_pk_mul_f32 v[128:129], v[128:129], v[186:187] op_sel_hi:[1,0]
	v_pk_mul_f32 v[130:131], v[130:131], v[186:187] op_sel_hi:[1,0]
	v_cvt_pk_bf16_f32 v140, v140, v141
	v_cvt_pk_bf16_f32 v141, v142, v143
	v_add_co_u32_e64 v142, s[0:1], s18, v146
	v_pk_mul_f32 v[128:129], v[0:1], v[128:129]
	v_pk_mul_f32 v[130:131], v[2:3], v[130:131]
	v_addc_co_u32_e64 v143, s[0:1], -1, v147, s[0:1]
	v_cvt_pk_bf16_f32 v128, v128, v129
	v_cvt_pk_bf16_f32 v129, v130, v131
	global_store_dwordx2 v[142:143], v[128:129], off offset:-2048
	v_mul_f32_e32 v128, 0x4b800000, v176
	v_cndmask_b32_e32 v128, v176, v128, vcc
	v_rsq_f32_e32 v128, v128
	v_pk_mul_f32 v[136:137], v[136:137], v[186:187] op_sel_hi:[1,0]
	v_pk_mul_f32 v[138:139], v[138:139], v[186:187] op_sel_hi:[1,0]
	v_pk_mul_f32 v[132:133], v[132:133], v[186:187] op_sel_hi:[1,0]
	v_mul_f32_e32 v129, 0x45800000, v128
	v_cndmask_b32_e32 v128, v128, v129, vcc
	v_pk_mul_f32 v[112:113], v[112:113], v[128:129] op_sel_hi:[1,0]
	v_pk_mul_f32 v[114:115], v[114:115], v[128:129] op_sel_hi:[1,0]
	v_pk_mul_f32 v[112:113], v[0:1], v[112:113]
	v_pk_mul_f32 v[114:115], v[2:3], v[114:115]
	v_pk_mul_f32 v[116:117], v[116:117], v[128:129] op_sel_hi:[1,0]
	v_pk_mul_f32 v[118:119], v[118:119], v[128:129] op_sel_hi:[1,0]
	v_cvt_pk_bf16_f32 v112, v112, v113
	v_cvt_pk_bf16_f32 v113, v114, v115
	v_add_co_u32_e32 v114, vcc, s24, v146
	v_pk_mul_f32 v[116:117], v[4:5], v[116:117]
	v_pk_mul_f32 v[118:119], v[6:7], v[118:119]
	v_addc_co_u32_e32 v115, vcc, -1, v147, vcc
	v_cvt_pk_bf16_f32 v116, v116, v117
	v_cvt_pk_bf16_f32 v117, v118, v119
	global_store_dwordx2 v[114:115], v[112:113], off offset:-4096
	v_mov_b32_e32 v112, v170
	v_mov_b32_e32 v113, v166
	v_mov_b32_e32 v166, v171
	global_store_dwordx2 v[142:143], v[116:117], off offset:-512
	v_pk_add_f32 v[112:113], v[112:113], v[166:167]
	v_mov_b32_e32 v116, v172
	v_mov_b32_e32 v117, v168
	v_pk_add_f32 v[112:113], v[112:113], v[116:117]
	v_mov_b32_e32 v168, v173
	v_pk_add_f32 v[112:113], v[112:113], v[168:169]
	ds_bpermute_b32 v117, v178, v113
	ds_bpermute_b32 v116, v178, v112
	v_pk_mul_f32 v[134:135], v[134:135], v[186:187] op_sel_hi:[1,0]
	v_pk_mul_f32 v[124:125], v[124:125], v[128:129] op_sel_hi:[1,0]
	v_pk_mul_f32 v[126:127], v[126:127], v[128:129] op_sel_hi:[1,0]
	v_pk_mul_f32 v[120:121], v[120:121], v[128:129] op_sel_hi:[1,0]
	s_waitcnt lgkmcnt(0)
; template <bool TO_BF16>
; DI void rms_rows(const int tid, const float* src, const float* gam, bf16_t* dst, float* fdst, int G, int c) {
;     ...
;         for (int o = 32; o > 0; o >>= 1)
; #pragma unroll
;             for (int q = 0; q < NR; ++q) s[q] += __shfl_xor(s[q], o);
; #pragma unroll
;         for (int q = 0; q < NR; ++q) { const float sc = rsqrtf(s[q] * (1.f / 1024.f) + 1e-6f);
; #pragma unroll
;             for (int k = 0; k < 4; ++k) {
;                 if (TO_BF16) { u32x2 o; o.x = pk2(v[q][k][0] * sc * g4[k][0], v[q][k][1] * sc * g4[k][1]); o.y = pk2(v[q][k][2] * sc * g4[k][2], v[q][k][3] * sc * g4[k][3]);
;                     *(u32x2*)(dst + (size_t)(r + q) * 1024 + k * 256 + lane * 4) = o; }
;                 else *(f32x4*)(fdst + (size_t)(r + q) * 1024 + k * 256 + lane * 4) = v[q][k] * sc * g4[k]; } }
	v_pk_add_f32 v[112:113], v[112:113], v[116:117]
	ds_bpermute_b32 v117, v179, v113
	ds_bpermute_b32 v116, v179, v112
	v_pk_mul_f32 v[122:123], v[122:123], v[128:129] op_sel_hi:[1,0]
	v_pk_mul_f32 v[136:137], v[8:9], v[136:137]
	v_pk_mul_f32 v[138:139], v[10:11], v[138:139]
	v_pk_mul_f32 v[132:133], v[4:5], v[132:133]
	s_waitcnt lgkmcnt(0)
	v_pk_add_f32 v[112:113], v[112:113], v[116:117]
	ds_bpermute_b32 v117, v180, v113
	ds_bpermute_b32 v116, v180, v112
	v_pk_mul_f32 v[134:135], v[6:7], v[134:135]
	v_pk_mul_f32 v[124:125], v[12:13], v[124:125]
	v_pk_mul_f32 v[126:127], v[14:15], v[126:127]
	v_pk_mul_f32 v[120:121], v[8:9], v[120:121]
	s_waitcnt lgkmcnt(0)
	v_pk_add_f32 v[112:113], v[112:113], v[116:117]
	ds_bpermute_b32 v117, v183, v113
	ds_bpermute_b32 v116, v183, v112
	v_pk_mul_f32 v[122:123], v[10:11], v[122:123]
	v_cvt_pk_bf16_f32 v136, v136, v137
	v_cvt_pk_bf16_f32 v137, v138, v139
	v_cvt_pk_bf16_f32 v132, v132, v133
	s_waitcnt lgkmcnt(0)
	v_pk_add_f32 v[112:113], v[112:113], v[116:117]
	ds_bpermute_b32 v117, v184, v113
	ds_bpermute_b32 v116, v184, v112
	v_cvt_pk_bf16_f32 v133, v134, v135
	v_cvt_pk_bf16_f32 v124, v124, v125
	v_cvt_pk_bf16_f32 v125, v126, v127
	v_cvt_pk_bf16_f32 v120, v120, v121
	s_waitcnt lgkmcnt(0)
	v_pk_add_f32 v[112:113], v[112:113], v[116:117]
	ds_bpermute_b32 v117, v185, v113
	ds_bpermute_b32 v116, v185, v112
	v_cvt_pk_bf16_f32 v121, v122, v123
	global_store_dwordx2 v[142:143], v[140:141], off offset:-3584
	global_store_dwordx2 v[142:143], v[136:137], off offset:-3072
	global_store_dwordx2 v[142:143], v[132:133], off offset:-2560
	s_waitcnt lgkmcnt(0)
	v_pk_add_f32 v[112:113], v[112:113], v[116:117]
	global_store_dwordx2 v[142:143], v[124:125], off offset:-1536
	v_pk_fma_f32 v[112:113], v[112:113], s[2:3], v[174:175] op_sel_hi:[1,0,0]
	global_store_dwordx2 v[142:143], v[120:121], off offset:-1024
	v_mul_f32_e32 v116, 0x4b800000, v113
	v_cmp_gt_f32_e64 s[0:1], s3, v113
	v_cmp_gt_f32_e32 vcc, s3, v112
	s_nop 0
	v_cndmask_b32_e64 v113, v113, v116, s[0:1]
	v_rsq_f32_e32 v113, v113
	s_nop 0
	v_mul_f32_e32 v116, 0x45800000, v113
	v_cndmask_b32_e64 v116, v113, v116, s[0:1]
	v_pk_mul_f32 v[96:97], v[96:97], v[116:117] op_sel_hi:[1,0]
	v_pk_mul_f32 v[98:99], v[98:99], v[116:117] op_sel_hi:[1,0]
	v_pk_mul_f32 v[96:97], v[0:1], v[96:97]
	v_pk_mul_f32 v[98:99], v[2:3], v[98:99]
	v_cvt_pk_bf16_f32 v96, v96, v97
	v_cvt_pk_bf16_f32 v97, v98, v99
	global_store_dwordx2 v[114:115], v[96:97], off offset:-2048
	v_mul_f32_e32 v96, 0x4b800000, v112
	v_cndmask_b32_e32 v96, v112, v96, vcc
	v_rsq_f32_e32 v96, v96
	v_pk_mul_f32 v[108:109], v[108:109], v[116:117] op_sel_hi:[1,0]
	v_pk_mul_f32 v[110:111], v[110:111], v[116:117] op_sel_hi:[1,0]
	v_pk_mul_f32 v[104:105], v[104:105], v[116:117] op_sel_hi:[1,0]
	v_mul_f32_e32 v97, 0x45800000, v96
	v_cndmask_b32_e32 v96, v96, v97, vcc
	v_pk_mul_f32 v[80:81], v[80:81], v[96:97] op_sel_hi:[1,0]
	v_pk_mul_f32 v[82:83], v[82:83], v[96:97] op_sel_hi:[1,0]
	v_pk_mul_f32 v[80:81], v[0:1], v[80:81]
	v_pk_mul_f32 v[82:83], v[2:3], v[82:83]
	v_cvt_pk_bf16_f32 v80, v80, v81
	v_cvt_pk_bf16_f32 v81, v82, v83
	global_store_dwordx2 v[114:115], v[80:81], off
	v_mov_b32_e32 v80, v162
	v_mov_b32_e32 v81, v158
	v_mov_b32_e32 v158, v163
	v_pk_add_f32 v[80:81], v[80:81], v[158:159]
	v_mov_b32_e32 v82, v164
	v_mov_b32_e32 v83, v160
	v_pk_add_f32 v[80:81], v[80:81], v[82:83]
	v_mov_b32_e32 v160, v165
	v_pk_add_f32 v[80:81], v[80:81], v[160:161]
	ds_bpermute_b32 v83, v178, v81
	ds_bpermute_b32 v82, v178, v80
	v_pk_mul_f32 v[106:107], v[106:107], v[116:117] op_sel_hi:[1,0]
	v_pk_mul_f32 v[100:101], v[100:101], v[116:117] op_sel_hi:[1,0]
	v_pk_mul_f32 v[102:103], v[102:103], v[116:117] op_sel_hi:[1,0]
	v_pk_mul_f32 v[92:93], v[92:93], v[96:97] op_sel_hi:[1,0]
	s_waitcnt lgkmcnt(0)
	v_pk_add_f32 v[80:81], v[80:81], v[82:83]
	ds_bpermute_b32 v83, v179, v81
	ds_bpermute_b32 v82, v179, v80
	v_pk_mul_f32 v[94:95], v[94:95], v[96:97] op_sel_hi:[1,0]
	v_pk_mul_f32 v[88:89], v[88:89], v[96:97] op_sel_hi:[1,0]
	v_pk_mul_f32 v[90:91], v[90:91], v[96:97] op_sel_hi:[1,0]
	v_pk_mul_f32 v[84:85], v[84:85], v[96:97] op_sel_hi:[1,0]
	s_waitcnt lgkmcnt(0)
	v_pk_add_f32 v[80:81], v[80:81], v[82:83]
	ds_bpermute_b32 v83, v180, v81
	ds_bpermute_b32 v82, v180, v80
	v_pk_mul_f32 v[86:87], v[86:87], v[96:97] op_sel_hi:[1,0]
	v_pk_mul_f32 v[108:109], v[12:13], v[108:109]
	v_pk_mul_f32 v[110:111], v[14:15], v[110:111]
	v_pk_mul_f32 v[104:105], v[8:9], v[104:105]
	s_waitcnt lgkmcnt(0)
	v_pk_add_f32 v[80:81], v[80:81], v[82:83]
	ds_bpermute_b32 v83, v183, v81
	ds_bpermute_b32 v82, v183, v80
	v_pk_mul_f32 v[106:107], v[10:11], v[106:107]
	v_pk_mul_f32 v[100:101], v[4:5], v[100:101]
	v_pk_mul_f32 v[102:103], v[6:7], v[102:103]
	v_pk_mul_f32 v[92:93], v[12:13], v[92:93]
	s_waitcnt lgkmcnt(0)
	v_pk_add_f32 v[80:81], v[80:81], v[82:83]
	ds_bpermute_b32 v83, v184, v81
	ds_bpermute_b32 v82, v184, v80
	v_pk_mul_f32 v[94:95], v[14:15], v[94:95]
	v_pk_mul_f32 v[88:89], v[8:9], v[88:89]
	v_pk_mul_f32 v[90:91], v[10:11], v[90:91]
	v_pk_mul_f32 v[84:85], v[4:5], v[84:85]
	s_waitcnt lgkmcnt(0)
	v_pk_add_f32 v[80:81], v[80:81], v[82:83]
	ds_bpermute_b32 v83, v185, v81
	ds_bpermute_b32 v82, v185, v80
	v_pk_mul_f32 v[86:87], v[6:7], v[86:87]
	v_cvt_pk_bf16_f32 v108, v108, v109
	v_cvt_pk_bf16_f32 v109, v110, v111
	v_cvt_pk_bf16_f32 v104, v104, v105
	s_waitcnt lgkmcnt(0)
; template <bool TO_BF16>
; DI void rms_rows(const int tid, const float* src, const float* gam, bf16_t* dst, float* fdst, int G, int c) {
;     ...
;         for (int o = 32; o > 0; o >>= 1)
; #pragma unroll
;             for (int q = 0; q < NR; ++q) s[q] += __shfl_xor(s[q], o);
; #pragma unroll
;         for (int q = 0; q < NR; ++q) { const float sc = rsqrtf(s[q] * (1.f / 1024.f) + 1e-6f);
; #pragma unroll
;             for (int k = 0; k < 4; ++k) {
;                 if (TO_BF16) { u32x2 o; o.x = pk2(v[q][k][0] * sc * g4[k][0], v[q][k][1] * sc * g4[k][1]); o.y = pk2(v[q][k][2] * sc * g4[k][2], v[q][k][3] * sc * g4[k][3]);
;                     *(u32x2*)(dst + (size_t)(r + q) * 1024 + k * 256 + lane * 4) = o; }
;                 else *(f32x4*)(fdst + (size_t)(r + q) * 1024 + k * 256 + lane * 4) = v[q][k] * sc * g4[k]; } }
	v_pk_add_f32 v[80:81], v[80:81], v[82:83]
	v_cvt_pk_bf16_f32 v105, v106, v107
	v_pk_fma_f32 v[80:81], v[80:81], s[2:3], v[174:175] op_sel_hi:[1,0,0]
	v_cvt_pk_bf16_f32 v100, v100, v101
	v_mul_f32_e32 v82, 0x4b800000, v81
	v_cmp_gt_f32_e64 s[0:1], s3, v81
	v_cmp_gt_f32_e32 vcc, s3, v80
	v_cvt_pk_bf16_f32 v101, v102, v103
	v_cndmask_b32_e64 v81, v81, v82, s[0:1]
	v_rsq_f32_e32 v81, v81
	v_cvt_pk_bf16_f32 v92, v92, v93
	v_cvt_pk_bf16_f32 v93, v94, v95
	v_cvt_pk_bf16_f32 v88, v88, v89
	v_mul_f32_e32 v82, 0x45800000, v81
	v_cndmask_b32_e64 v82, v81, v82, s[0:1]
	v_pk_mul_f32 v[76:77], v[76:77], v[82:83] op_sel_hi:[1,0]
	v_pk_mul_f32 v[78:79], v[78:79], v[82:83] op_sel_hi:[1,0]
	v_pk_mul_f32 v[76:77], v[12:13], v[76:77]
	v_pk_mul_f32 v[78:79], v[14:15], v[78:79]
	v_pk_mul_f32 v[48:49], v[48:49], v[82:83] op_sel_hi:[1,0]
	v_pk_mul_f32 v[50:51], v[50:51], v[82:83] op_sel_hi:[1,0]
	v_cvt_pk_bf16_f32 v76, v76, v77
	v_cvt_pk_bf16_f32 v77, v78, v79
	v_add_co_u32_e64 v78, s[0:1], s25, v146
	v_pk_mul_f32 v[48:49], v[0:1], v[48:49]
	v_pk_mul_f32 v[50:51], v[2:3], v[50:51]
	v_addc_co_u32_e64 v79, s[0:1], -1, v147, s[0:1]
	v_cvt_pk_bf16_f32 v48, v48, v49
	v_cvt_pk_bf16_f32 v49, v50, v51
	global_store_dwordx2 v[78:79], v[48:49], off offset:-2048
	v_mul_f32_e32 v48, 0x4b800000, v80
	v_cndmask_b32_e32 v48, v80, v48, vcc
	v_rsq_f32_e32 v48, v48
	v_pk_mul_f32 v[56:57], v[56:57], v[82:83] op_sel_hi:[1,0]
	v_pk_mul_f32 v[58:59], v[58:59], v[82:83] op_sel_hi:[1,0]
	v_pk_mul_f32 v[52:53], v[52:53], v[82:83] op_sel_hi:[1,0]
	v_mul_f32_e32 v49, 0x45800000, v48
	v_cndmask_b32_e32 v48, v48, v49, vcc
	v_pk_mul_f32 v[32:33], v[32:33], v[48:49] op_sel_hi:[1,0]
	v_pk_mul_f32 v[34:35], v[34:35], v[48:49] op_sel_hi:[1,0]
	v_pk_mul_f32 v[32:33], v[0:1], v[32:33]
	v_pk_mul_f32 v[34:35], v[2:3], v[34:35]
	v_cvt_pk_bf16_f32 v32, v32, v33
	v_cvt_pk_bf16_f32 v33, v34, v35
	global_store_dwordx2 v[146:147], v[32:33], off offset:-4096
	v_mov_b32_e32 v32, v154
	v_mov_b32_e32 v33, v150
	v_mov_b32_e32 v150, v155
	v_pk_add_f32 v[32:33], v[32:33], v[150:151]
	v_mov_b32_e32 v34, v156
	v_mov_b32_e32 v35, v152
	v_pk_add_f32 v[32:33], v[32:33], v[34:35]
	v_mov_b32_e32 v152, v157
	v_pk_add_f32 v[32:33], v[32:33], v[152:153]
	ds_bpermute_b32 v35, v178, v33
	ds_bpermute_b32 v34, v178, v32
	v_pk_mul_f32 v[54:55], v[54:55], v[82:83] op_sel_hi:[1,0]
	v_pk_mul_f32 v[44:45], v[44:45], v[48:49] op_sel_hi:[1,0]
	v_pk_mul_f32 v[46:47], v[46:47], v[48:49] op_sel_hi:[1,0]
	v_pk_mul_f32 v[40:41], v[40:41], v[48:49] op_sel_hi:[1,0]
	s_waitcnt lgkmcnt(0)
	v_pk_add_f32 v[32:33], v[32:33], v[34:35]
	ds_bpermute_b32 v35, v179, v33
	ds_bpermute_b32 v34, v179, v32
	v_pk_mul_f32 v[42:43], v[42:43], v[48:49] op_sel_hi:[1,0]
	v_pk_mul_f32 v[36:37], v[36:37], v[48:49] op_sel_hi:[1,0]
	v_pk_mul_f32 v[38:39], v[38:39], v[48:49] op_sel_hi:[1,0]
	v_pk_mul_f32 v[56:57], v[8:9], v[56:57]
	s_waitcnt lgkmcnt(0)
	v_pk_add_f32 v[32:33], v[32:33], v[34:35]
	ds_bpermute_b32 v35, v180, v33
	ds_bpermute_b32 v34, v180, v32
	v_pk_mul_f32 v[58:59], v[10:11], v[58:59]
	v_pk_mul_f32 v[52:53], v[4:5], v[52:53]
	v_pk_mul_f32 v[54:55], v[6:7], v[54:55]
	v_pk_mul_f32 v[44:45], v[12:13], v[44:45]
	s_waitcnt lgkmcnt(0)
	v_pk_add_f32 v[32:33], v[32:33], v[34:35]
	ds_bpermute_b32 v35, v183, v33
	ds_bpermute_b32 v34, v183, v32
	v_pk_mul_f32 v[46:47], v[14:15], v[46:47]
	v_pk_mul_f32 v[40:41], v[8:9], v[40:41]
	v_pk_mul_f32 v[42:43], v[10:11], v[42:43]
	v_pk_mul_f32 v[36:37], v[4:5], v[36:37]
	s_waitcnt lgkmcnt(0)
	v_pk_add_f32 v[32:33], v[32:33], v[34:35]
	ds_bpermute_b32 v35, v184, v33
	ds_bpermute_b32 v34, v184, v32
	v_pk_mul_f32 v[38:39], v[6:7], v[38:39]
	v_cvt_pk_bf16_f32 v89, v90, v91
	v_cvt_pk_bf16_f32 v84, v84, v85
	v_cvt_pk_bf16_f32 v85, v86, v87
	s_waitcnt lgkmcnt(0)
	v_pk_add_f32 v[32:33], v[32:33], v[34:35]
	ds_bpermute_b32 v35, v185, v33
	ds_bpermute_b32 v34, v185, v32
	v_cvt_pk_bf16_f32 v56, v56, v57
	v_cvt_pk_bf16_f32 v57, v58, v59
	v_cvt_pk_bf16_f32 v52, v52, v53
	v_cvt_pk_bf16_f32 v53, v54, v55
	s_waitcnt lgkmcnt(0)
; template <bool TO_BF16>
; DI void rms_rows(const int tid, const float* src, const float* gam, bf16_t* dst, float* fdst, int G, int c) {
;     ...
;     for (int r = (c * 8 + wave) * NR; r < MTOK; r += G * 8 * NR) {
;         f32x4 v[NR][4]; float s[NR];
; #pragma unroll
;         for (int q = 0; q < NR; ++q)
; #pragma unroll
;             for (int k = 0; k < 4; ++k) v[q][k] = *(const f32x4*)(src + (size_t)(r + q) * 1024 + k * 256 + lane * 4);
; #pragma unroll
;         for (int q = 0; q < NR; ++q) { s[q] = 0.f;
; #pragma unroll
;             for (int k = 0; k < 4; ++k) s[q] += v[q][k][0] * v[q][k][0] + v[q][k][1] * v[q][k][1] + v[q][k][2] * v[q][k][2] + v[q][k][3] * v[q][k][3]; }
; #pragma unroll
;         for (int o = 32; o > 0; o >>= 1)
; #pragma unroll
;             for (int q = 0; q < NR; ++q) s[q] += __shfl_xor(s[q], o);
; #pragma unroll
;         for (int q = 0; q < NR; ++q) { const float sc = rsqrtf(s[q] * (1.f / 1024.f) + 1e-6f);
; #pragma unroll
;             for (int k = 0; k < 4; ++k) {
;                 if (TO_BF16) { u32x2 o; o.x = pk2(v[q][k][0] * sc * g4[k][0], v[q][k][1] * sc * g4[k][1]); o.y = pk2(v[q][k][2] * sc * g4[k][2], v[q][k][3] * sc * g4[k][3]);
;                     *(u32x2*)(dst + (size_t)(r + q) * 1024 + k * 256 + lane * 4) = o; }
;                 else *(f32x4*)(fdst + (size_t)(r + q) * 1024 + k * 256 + lane * 4) = v[q][k] * sc * g4[k]; } }
	v_pk_add_f32 v[32:33], v[32:33], v[34:35]
	v_cvt_pk_bf16_f32 v44, v44, v45
	v_pk_fma_f32 v[32:33], v[32:33], s[2:3], v[174:175] op_sel_hi:[1,0,0]
	v_cvt_pk_bf16_f32 v45, v46, v47
	v_mul_f32_e32 v34, 0x4b800000, v33
	v_cmp_gt_f32_e64 s[0:1], s3, v33
	v_cmp_gt_f32_e32 vcc, s3, v32
	v_cvt_pk_bf16_f32 v40, v40, v41
	v_cndmask_b32_e64 v33, v33, v34, s[0:1]
	v_rsq_f32_e32 v33, v33
	v_cvt_pk_bf16_f32 v41, v42, v43
	v_cvt_pk_bf16_f32 v36, v36, v37
	v_cvt_pk_bf16_f32 v37, v38, v39
	v_mul_f32_e32 v34, 0x45800000, v33
	v_cndmask_b32_e64 v34, v33, v34, s[0:1]
	v_pk_mul_f32 v[16:17], v[16:17], v[34:35] op_sel_hi:[1,0]
	v_pk_mul_f32 v[18:19], v[18:19], v[34:35] op_sel_hi:[1,0]
	v_pk_mul_f32 v[16:17], v[0:1], v[16:17]
	v_pk_mul_f32 v[18:19], v[2:3], v[18:19]
	v_cvt_pk_bf16_f32 v16, v16, v17
	v_cvt_pk_bf16_f32 v17, v18, v19
	global_store_dwordx2 v[146:147], v[16:17], off offset:-2048
	v_mul_f32_e32 v16, 0x4b800000, v32
	v_cndmask_b32_e32 v16, v32, v16, vcc
	v_rsq_f32_e32 v16, v16
	v_pk_mul_f32 v[20:21], v[20:21], v[34:35] op_sel_hi:[1,0]
	v_pk_mul_f32 v[22:23], v[22:23], v[34:35] op_sel_hi:[1,0]
	v_pk_mul_f32 v[20:21], v[4:5], v[20:21]
	v_pk_mul_f32 v[22:23], v[6:7], v[22:23]
	v_mul_f32_e32 v17, 0x45800000, v16
	v_cvt_pk_bf16_f32 v20, v20, v21
	v_cvt_pk_bf16_f32 v21, v22, v23
	v_cndmask_b32_e32 v16, v16, v17, vcc
	global_store_dwordx2 v[146:147], v[20:21], off offset:-2560
	v_pk_mul_f32 v[18:19], v[72:73], v[16:17] op_sel_hi:[1,0]
	v_pk_mul_f32 v[20:21], v[74:75], v[16:17] op_sel_hi:[1,0]
	v_pk_mul_f32 v[18:19], v[12:13], v[18:19]
	v_pk_mul_f32 v[20:21], v[14:15], v[20:21]
	v_cvt_pk_bf16_f32 v18, v18, v19
	v_cvt_pk_bf16_f32 v19, v20, v21
	global_store_dwordx2 v[146:147], v[18:19], off offset:-1536
	v_pk_mul_f32 v[18:19], v[68:69], v[16:17] op_sel_hi:[1,0]
	v_pk_mul_f32 v[20:21], v[70:71], v[16:17] op_sel_hi:[1,0]
	v_pk_mul_f32 v[18:19], v[8:9], v[18:19]
	v_pk_mul_f32 v[20:21], v[10:11], v[20:21]
	v_cvt_pk_bf16_f32 v18, v18, v19
	v_cvt_pk_bf16_f32 v19, v20, v21
	global_store_dwordx2 v[146:147], v[18:19], off offset:-1024
	v_pk_mul_f32 v[18:19], v[64:65], v[16:17] op_sel_hi:[1,0]
	v_pk_mul_f32 v[20:21], v[66:67], v[16:17] op_sel_hi:[1,0]
	v_pk_mul_f32 v[18:19], v[4:5], v[18:19]
	v_pk_mul_f32 v[20:21], v[6:7], v[20:21]
	v_cvt_pk_bf16_f32 v18, v18, v19
	v_cvt_pk_bf16_f32 v19, v20, v21
	v_pk_mul_f32 v[28:29], v[28:29], v[34:35] op_sel_hi:[1,0]
	v_pk_mul_f32 v[30:31], v[30:31], v[34:35] op_sel_hi:[1,0]
	v_pk_mul_f32 v[24:25], v[24:25], v[34:35] op_sel_hi:[1,0]
	v_pk_mul_f32 v[26:27], v[26:27], v[34:35] op_sel_hi:[1,0]
	global_store_dwordx2 v[146:147], v[18:19], off offset:-512
	v_pk_mul_f32 v[18:19], v[60:61], v[16:17] op_sel_hi:[1,0]
	v_pk_mul_f32 v[16:17], v[62:63], v[16:17] op_sel_hi:[1,0]
	v_pk_mul_f32 v[28:29], v[12:13], v[28:29]
	v_pk_mul_f32 v[30:31], v[14:15], v[30:31]
	v_pk_mul_f32 v[24:25], v[8:9], v[24:25]
	v_pk_mul_f32 v[26:27], v[10:11], v[26:27]
	v_pk_mul_f32 v[18:19], v[0:1], v[18:19]
	v_pk_mul_f32 v[16:17], v[2:3], v[16:17]
	v_cvt_pk_bf16_f32 v28, v28, v29
	v_cvt_pk_bf16_f32 v29, v30, v31
	v_cvt_pk_bf16_f32 v24, v24, v25
	v_cvt_pk_bf16_f32 v25, v26, v27
	v_cvt_pk_bf16_f32 v18, v18, v19
	v_cvt_pk_bf16_f32 v19, v16, v17
	v_cmp_lt_i32_e32 vcc, s70, v144
	global_store_dwordx2 v[146:147], v[28:29], off offset:-3584
	global_store_dwordx2 v[146:147], v[24:25], off offset:-3072
	global_store_dwordx2 v[146:147], v[18:19], off
	v_bfe_u32 v146, v144, 11, 3
	v_lshrrev_b32_e32 v147, 14, v144
	v_sub_u32_e32 v147, 3, v147
	v_lshlrev_b32_e32 v147, 11, v147
	v_lshl_or_b32 v146, v146, 13, v147
	v_and_b32_e32 v147, 0x7ff, v144
	v_or_b32_e32 v146, v146, v147
	v_lshlrev_b32_e32 v146, 11, v146
	v_and_b32_e32 v147, 63, v182
	v_lshl_or_b32 v146, v147, 3, v146
	v_mov_b32_e32 v147, 0
	v_lshl_add_u64 v[146:147], s[100:101], 0, v[146:147]
	s_or_b64 s[14:15], vcc, s[14:15]
	global_store_dwordx2 v[114:115], v[108:109], off offset:-3584
	global_store_dwordx2 v[114:115], v[104:105], off offset:-3072
	global_store_dwordx2 v[114:115], v[100:101], off offset:-2560
	global_store_dwordx2 v[114:115], v[92:93], off offset:-1536
	global_store_dwordx2 v[114:115], v[88:89], off offset:-1024
	global_store_dwordx2 v[114:115], v[84:85], off offset:-512
	global_store_dwordx2 v[78:79], v[76:77], off offset:-3584
	global_store_dwordx2 v[78:79], v[56:57], off offset:-3072
	global_store_dwordx2 v[78:79], v[52:53], off offset:-2560
	global_store_dwordx2 v[78:79], v[44:45], off offset:-1536
	global_store_dwordx2 v[78:79], v[40:41], off offset:-1024
	global_store_dwordx2 v[78:79], v[36:37], off offset:-512
	s_andn2_b64 exec, exec, s[14:15]
	s_cbranch_execnz .LBB0_70

; template <bool TO_BF16>
; DI void rms_rows(const int tid, const float* src, const float* gam, bf16_t* dst, float* fdst, int G, int c) {
;     ...
;     const int wave = tid >> 6, lane = tid & 63;
;     f32x4 g4[4];
; #pragma unroll
;     for (int k = 0; k < 4; ++k) g4[k] = *(const f32x4*)(gam + k * 256 + lane * 4);
;     for (int r = (c * 8 + wave) * NR; r < MTOK; r += G * 8 * NR) {
;         f32x4 v[NR][4]; float s[NR];
; #pragma unroll
;         for (int q = 0; q < NR; ++q)
; #pragma unroll
;             for (int k = 0; k < 4; ++k) v[q][k] = *(const f32x4*)(src + (size_t)(r + q) * 1024 + k * 256 + lane * 4);
; DI void rms_final(const int tid, float* io, const float* gam, int G, int c) { rms_rows<false>(tid, io, gam, nullptr, io, G, c); }
.LBB0_72:
	s_andn2_b64 vcc, exec, s[4:5]
	s_cbranch_vccnz .LBB0_84
	s_cmp_eq_u32 s64, 24
	s_cbranch_scc0 .LBB0_84
	v_ashrrev_i32_e32 v0, 3, v182
	v_and_b32_e32 v0, -8, v0
	v_readlane_b32 s0, v250, 0
	s_nop 1
	v_add_u32_e32 v144, s0, v0
	s_mov_b32 s0, 0x10000
	v_cmp_gt_i32_e32 vcc, s0, v144
	s_and_saveexec_b64 s[0:1], vcc
	s_mov_b32 s14, 0x358637bd
	s_cbranch_execz .LBB0_77
	v_lshlrev_b32_e32 v0, 4, v182
	v_and_b32_e32 v12, 0x3f0, v0
	global_load_dwordx4 v[0:3], v12, s[50:51]
	global_load_dwordx4 v[4:7], v12, s[50:51] offset:1024
	global_load_dwordx4 v[8:11], v12, s[50:51] offset:2048
	s_nop 0
	global_load_dwordx4 v[12:15], v12, s[50:51] offset:3072
	v_and_b32_e32 v16, 64, v234
	v_add_u32_e32 v16, 64, v16
	v_xor_b32_e32 v17, 32, v234
	v_cmp_lt_i32_e32 vcc, v17, v16
	v_ashrrev_i32_e32 v145, 31, v144
	v_and_b32_e32 v18, 63, v182
	v_cndmask_b32_e32 v17, v234, v17, vcc
	v_lshlrev_b32_e32 v180, 2, v17
	v_xor_b32_e32 v17, 16, v234
	v_cmp_lt_i32_e32 vcc, v17, v16
	v_readlane_b32 s4, v253, 4
	v_readlane_b32 s5, v253, 5
	v_cndmask_b32_e32 v17, v234, v17, vcc
	v_lshlrev_b32_e32 v183, 2, v17
	v_xor_b32_e32 v17, 8, v234
	v_cmp_lt_i32_e32 vcc, v17, v16
	s_nop 1
	v_cndmask_b32_e32 v17, v234, v17, vcc
	v_lshlrev_b32_e32 v192, 2, v17
	v_xor_b32_e32 v17, 4, v234
	v_cmp_lt_i32_e32 vcc, v17, v16
	s_nop 1
	v_cndmask_b32_e32 v17, v234, v17, vcc
	v_lshlrev_b32_e32 v193, 2, v17
	v_xor_b32_e32 v17, 2, v234
	v_cmp_lt_i32_e32 vcc, v17, v16
	s_nop 1
	v_cndmask_b32_e32 v17, v234, v17, vcc
	v_lshlrev_b32_e32 v194, 2, v17
	v_xor_b32_e32 v17, 1, v234
	v_cmp_lt_i32_e32 vcc, v17, v16
	s_nop 1
	v_cndmask_b32_e32 v16, v234, v17, vcc
	v_lshlrev_b32_e32 v195, 2, v16
	v_lshlrev_b64 v[16:17], 12, v[144:145]
	v_lshl_or_b32 v16, v18, 4, v16
	v_lshl_add_u64 v[146:147], s[4:5], 0, v[16:17]
	s_mov_b64 s[4:5], 0
	v_readlane_b32 s98, v253, 4
	v_readlane_b32 s99, v253, 5
	s_nop 3
	v_bfe_u32 v146, v144, 11, 3
	v_lshrrev_b32_e32 v147, 14, v144
	v_sub_u32_e32 v147, 3, v147
	v_lshlrev_b32_e32 v147, 11, v147
	v_lshl_or_b32 v146, v146, 13, v147
	v_and_b32_e32 v147, 0x7ff, v144
	v_or_b32_e32 v146, v146, v147
	v_lshlrev_b32_e32 v146, 12, v146
	v_and_b32_e32 v147, 63, v182
	v_lshl_or_b32 v146, v147, 4, v146
	v_mov_b32_e32 v147, 0
	v_lshl_add_u64 v[146:147], s[98:99], 0, v[146:147]
.LBB0_76:
	v_add_co_u32_e32 v160, vcc, 0xffff9000, v146
	v_add_u32_e32 v144, s66, v144
	s_nop 0
	v_addc_co_u32_e32 v161, vcc, -1, v147, vcc
	global_load_dwordx4 v[140:143], v[160:161], off offset:-3072
	global_load_dwordx4 v[136:139], v[160:161], off offset:-2048
	global_load_dwordx4 v[132:135], v[160:161], off offset:-1024
	global_load_dwordx4 v[128:131], v[160:161], off
	v_add_co_u32_e32 v158, vcc, 0xffffa000, v146
	s_waitcnt vmcnt(0)
	v_mov_b32_e32 v164, v141
	v_addc_co_u32_e32 v159, vcc, -1, v147, vcc
	global_load_dwordx4 v[104:107], v[158:159], off offset:-3072
	global_load_dwordx4 v[96:99], v[158:159], off offset:-2048
	global_load_dwordx4 v[28:31], v[146:147], off offset:-3072
	global_load_dwordx4 v[24:27], v[146:147], off offset:-2048
	global_load_dwordx4 v[20:23], v[146:147], off offset:-1024
	global_load_dwordx4 v[16:19], v[146:147], off
	global_load_dwordx4 v[124:127], v[158:159], off offset:-1024
	global_load_dwordx4 v[120:123], v[158:159], off
	v_add_co_u32_e32 v156, vcc, 0xffffb000, v146
	s_waitcnt vmcnt(10)
	v_mov_b32_e32 v165, v137
	v_addc_co_u32_e32 v157, vcc, -1, v147, vcc
	global_load_dwordx4 v[116:119], v[156:157], off offset:-3072
	global_load_dwordx4 v[112:115], v[156:157], off offset:-2048
	global_load_dwordx4 v[108:111], v[156:157], off offset:-1024
	global_load_dwordx4 v[100:103], v[156:157], off
	v_add_co_u32_e32 v154, vcc, 0xffffc000, v146
	v_mov_b32_e32 v162, v140
	s_nop 0
	v_addc_co_u32_e32 v155, vcc, -1, v147, vcc
	global_load_dwordx4 v[92:95], v[154:155], off offset:-3072
	global_load_dwordx4 v[88:91], v[154:155], off offset:-2048
	global_load_dwordx4 v[84:87], v[154:155], off offset:-1024
	global_load_dwordx4 v[80:83], v[154:155], off
	v_add_co_u32_e32 v152, vcc, 0xffffd000, v146
	v_mov_b32_e32 v163, v136
	s_nop 0
	v_addc_co_u32_e32 v153, vcc, -1, v147, vcc
	global_load_dwordx4 v[76:79], v[152:153], off offset:-3072
	global_load_dwordx4 v[72:75], v[152:153], off offset:-2048
	global_load_dwordx4 v[68:71], v[152:153], off offset:-1024
	global_load_dwordx4 v[64:67], v[152:153], off
	v_add_co_u32_e32 v150, vcc, 0xffffe000, v146
	s_waitcnt vmcnt(21)
	v_mov_b32_e32 v172, v133
	v_addc_co_u32_e32 v151, vcc, -1, v147, vcc
	global_load_dwordx4 v[60:63], v[150:151], off offset:-3072
	global_load_dwordx4 v[56:59], v[150:151], off offset:-2048
	global_load_dwordx4 v[52:55], v[150:151], off offset:-1024
	global_load_dwordx4 v[44:47], v[150:151], off
	v_add_co_u32_e32 v148, vcc, 0xfffff000, v146
	s_waitcnt vmcnt(24)
	v_mov_b32_e32 v173, v129
	v_addc_co_u32_e32 v149, vcc, -1, v147, vcc
	global_load_dwordx4 v[40:43], v[148:149], off offset:-3072
	global_load_dwordx4 v[36:39], v[148:149], off offset:-2048
	global_load_dwordx4 v[32:35], v[148:149], off offset:-1024
	global_load_dwordx4 v[48:51], v[146:147], off offset:-4096
	v_pk_mul_f32 v[164:165], v[164:165], v[164:165]
	v_mov_b32_e32 v166, v142
	v_mov_b32_e32 v167, v138
	v_mov_b32_e32 v170, v132
	v_mov_b32_e32 v171, v128
	v_pk_mul_f32 v[172:173], v[172:173], v[172:173]
	v_pk_fma_f32 v[162:163], v[162:163], v[162:163], v[164:165]
	v_mov_b32_e32 v168, v143
	v_mov_b32_e32 v169, v139
	v_mov_b32_e32 v174, v134
	v_mov_b32_e32 v175, v130
	v_pk_fma_f32 v[164:165], v[170:171], v[170:171], v[172:173]
	v_pk_fma_f32 v[162:163], v[166:167], v[166:167], v[162:163]
	s_waitcnt vmcnt(0)
; template <bool TO_BF16>
; DI void rms_rows(const int tid, const float* src, const float* gam, bf16_t* dst, float* fdst, int G, int c) {
;     ...
;         for (int q = 0; q < NR; ++q)
; #pragma unroll
;             for (int k = 0; k < 4; ++k) v[q][k] = *(const f32x4*)(src + (size_t)(r + q) * 1024 + k * 256 + lane * 4);
; #pragma unroll
;         for (int q = 0; q < NR; ++q) { s[q] = 0.f;
; #pragma unroll
;             for (int k = 0; k < 4; ++k) s[q] += v[q][k][0] * v[q][k][0] + v[q][k][1] * v[q][k][1] + v[q][k][2] * v[q][k][2] + v[q][k][3] * v[q][k][3]; }
; #pragma unroll
;         for (int o = 32; o > 0; o >>= 1)
; #pragma unroll
;             for (int q = 0; q < NR; ++q) s[q] += __shfl_xor(s[q], o);
	v_mov_b32_e32 v170, v69
	v_pk_fma_f32 v[166:167], v[168:169], v[168:169], v[162:163]
	v_pk_fma_f32 v[162:163], v[174:175], v[174:175], v[164:165]
	v_mov_b32_e32 v164, v135
	v_mov_b32_e32 v165, v131
	v_mov_b32_e32 v168, v105
	v_mov_b32_e32 v169, v97
	v_pk_fma_f32 v[164:165], v[164:165], v[164:165], v[162:163]
	v_mov_b32_e32 v162, v104
	v_mov_b32_e32 v163, v96
	v_pk_mul_f32 v[168:169], v[168:169], v[168:169]
	s_waitcnt vmcnt(8)
	v_mov_b32_e32 v171, v65
	v_pk_fma_f32 v[162:163], v[162:163], v[162:163], v[168:169]
	v_mov_b32_e32 v168, v106
	v_mov_b32_e32 v169, v98
	v_pk_fma_f32 v[162:163], v[168:169], v[168:169], v[162:163]
	v_mov_b32_e32 v168, v107
	v_mov_b32_e32 v169, v99
	v_pk_fma_f32 v[172:173], v[168:169], v[168:169], v[162:163]
	v_mov_b32_e32 v168, v125
	v_mov_b32_e32 v169, v121
	v_mov_b32_e32 v162, v124
	v_mov_b32_e32 v163, v120
	v_pk_mul_f32 v[168:169], v[168:169], v[168:169]
	v_pk_mul_f32 v[170:171], v[170:171], v[170:171]
	v_pk_fma_f32 v[162:163], v[162:163], v[162:163], v[168:169]
	v_mov_b32_e32 v168, v126
	v_mov_b32_e32 v169, v122
	v_pk_fma_f32 v[162:163], v[168:169], v[168:169], v[162:163]
	v_mov_b32_e32 v168, v127
	v_mov_b32_e32 v169, v123
	v_pk_fma_f32 v[178:179], v[168:169], v[168:169], v[162:163]
	v_mov_b32_e32 v168, v117
	v_mov_b32_e32 v169, v113
	v_mov_b32_e32 v162, v116
	v_mov_b32_e32 v163, v112
	v_pk_mul_f32 v[168:169], v[168:169], v[168:169]
	s_waitcnt vmcnt(7)
	v_mov_b32_e32 v174, v61
	v_pk_fma_f32 v[162:163], v[162:163], v[162:163], v[168:169]
	v_mov_b32_e32 v168, v118
	v_mov_b32_e32 v169, v114
	v_pk_fma_f32 v[162:163], v[168:169], v[168:169], v[162:163]
	v_mov_b32_e32 v168, v119
	v_mov_b32_e32 v169, v115
	v_pk_fma_f32 v[184:185], v[168:169], v[168:169], v[162:163]
	v_mov_b32_e32 v168, v109
	v_mov_b32_e32 v169, v101
	v_mov_b32_e32 v162, v108
	v_mov_b32_e32 v163, v100
	v_pk_mul_f32 v[168:169], v[168:169], v[168:169]
	s_waitcnt vmcnt(6)
	v_mov_b32_e32 v175, v57
	v_pk_fma_f32 v[162:163], v[162:163], v[162:163], v[168:169]
	v_mov_b32_e32 v168, v110
	v_mov_b32_e32 v169, v102
	v_pk_fma_f32 v[162:163], v[168:169], v[168:169], v[162:163]
	v_mov_b32_e32 v168, v111
	v_mov_b32_e32 v169, v103
	v_pk_fma_f32 v[186:187], v[168:169], v[168:169], v[162:163]
	v_mov_b32_e32 v168, v93
	v_mov_b32_e32 v169, v89
	v_mov_b32_e32 v162, v92
	v_mov_b32_e32 v163, v88
	v_pk_mul_f32 v[168:169], v[168:169], v[168:169]
	v_pk_mul_f32 v[174:175], v[174:175], v[174:175]
	v_pk_fma_f32 v[162:163], v[162:163], v[162:163], v[168:169]
	v_mov_b32_e32 v168, v94
	v_mov_b32_e32 v169, v90
	v_pk_fma_f32 v[162:163], v[168:169], v[168:169], v[162:163]
	v_mov_b32_e32 v168, v95
	v_mov_b32_e32 v169, v91
	v_pk_fma_f32 v[188:189], v[168:169], v[168:169], v[162:163]
	v_mov_b32_e32 v168, v85
	v_mov_b32_e32 v169, v81
	v_mov_b32_e32 v162, v84
	v_mov_b32_e32 v163, v80
	v_pk_mul_f32 v[168:169], v[168:169], v[168:169]
	s_waitcnt vmcnt(5)
	v_mov_b32_e32 v176, v53
	v_pk_fma_f32 v[162:163], v[162:163], v[162:163], v[168:169]
	v_mov_b32_e32 v168, v86
	v_mov_b32_e32 v169, v82
	v_pk_fma_f32 v[162:163], v[168:169], v[168:169], v[162:163]
	v_mov_b32_e32 v168, v87
	v_mov_b32_e32 v169, v83
	v_pk_fma_f32 v[190:191], v[168:169], v[168:169], v[162:163]
	v_mov_b32_e32 v168, v77
	v_mov_b32_e32 v169, v73
	v_mov_b32_e32 v162, v76
	v_mov_b32_e32 v163, v72
	v_pk_mul_f32 v[168:169], v[168:169], v[168:169]
	s_waitcnt vmcnt(4)
	v_mov_b32_e32 v177, v45
	v_pk_fma_f32 v[162:163], v[162:163], v[162:163], v[168:169]
	v_mov_b32_e32 v168, v78
	v_mov_b32_e32 v169, v74
	v_pk_fma_f32 v[162:163], v[168:169], v[168:169], v[162:163]
	v_mov_b32_e32 v168, v79
	v_mov_b32_e32 v169, v75
	v_pk_fma_f32 v[168:169], v[168:169], v[168:169], v[162:163]
	v_mov_b32_e32 v162, v68
	v_mov_b32_e32 v163, v64
	v_pk_fma_f32 v[162:163], v[162:163], v[162:163], v[170:171]
	v_mov_b32_e32 v170, v70
	v_mov_b32_e32 v171, v66
	v_pk_fma_f32 v[162:163], v[170:171], v[170:171], v[162:163]
	v_mov_b32_e32 v170, v71
	v_mov_b32_e32 v171, v67
	v_pk_fma_f32 v[170:171], v[170:171], v[170:171], v[162:163]
	v_mov_b32_e32 v162, v60
	v_mov_b32_e32 v163, v56
	v_pk_fma_f32 v[162:163], v[162:163], v[162:163], v[174:175]
	v_mov_b32_e32 v174, v62
	v_mov_b32_e32 v175, v58
	v_pk_fma_f32 v[162:163], v[174:175], v[174:175], v[162:163]
	v_mov_b32_e32 v174, v63
	v_mov_b32_e32 v175, v59
	v_pk_fma_f32 v[174:175], v[174:175], v[174:175], v[162:163]
	v_mov_b32_e32 v162, v52
	v_mov_b32_e32 v163, v44
	v_pk_mul_f32 v[176:177], v[176:177], v[176:177]
	s_waitcnt vmcnt(3)
	v_mov_b32_e32 v196, v41
	v_pk_fma_f32 v[162:163], v[162:163], v[162:163], v[176:177]
	v_mov_b32_e32 v176, v54
	v_mov_b32_e32 v177, v46
	v_pk_fma_f32 v[162:163], v[176:177], v[176:177], v[162:163]
	v_mov_b32_e32 v176, v55
	v_mov_b32_e32 v177, v47
	s_waitcnt vmcnt(2)
	v_mov_b32_e32 v197, v37
	v_pk_fma_f32 v[176:177], v[176:177], v[176:177], v[162:163]
	v_mov_b32_e32 v162, v40
	v_mov_b32_e32 v163, v36
	v_pk_mul_f32 v[196:197], v[196:197], v[196:197]
	s_waitcnt vmcnt(1)
	v_mov_b32_e32 v198, v33
	v_pk_fma_f32 v[162:163], v[162:163], v[162:163], v[196:197]
	v_mov_b32_e32 v196, v42
	v_mov_b32_e32 v197, v38
	v_pk_fma_f32 v[162:163], v[196:197], v[196:197], v[162:163]
	v_mov_b32_e32 v196, v43
	v_mov_b32_e32 v197, v39
	s_waitcnt vmcnt(0)
	v_mov_b32_e32 v199, v49
	v_pk_fma_f32 v[162:163], v[196:197], v[196:197], v[162:163]
	v_mov_b32_e32 v196, v32
	v_mov_b32_e32 v197, v48
	v_pk_mul_f32 v[198:199], v[198:199], v[198:199]
	s_nop 0
	v_pk_fma_f32 v[196:197], v[196:197], v[196:197], v[198:199]
	v_mov_b32_e32 v198, v34
	v_mov_b32_e32 v199, v50
	v_pk_fma_f32 v[196:197], v[198:199], v[198:199], v[196:197]
	v_mov_b32_e32 v198, v172
	v_mov_b32_e32 v199, v166
	v_mov_b32_e32 v166, v173
	v_pk_add_f32 v[166:167], v[198:199], v[166:167]
	v_mov_b32_e32 v172, v178
	v_mov_b32_e32 v173, v164
	v_pk_add_f32 v[166:167], v[166:167], v[172:173]
	v_mov_b32_e32 v164, v179
	v_pk_add_f32 v[164:165], v[166:167], v[164:165]
	ds_bpermute_b32 v173, v180, v165
	ds_bpermute_b32 v172, v180, v164
	v_mov_b32_e32 v166, v35
	v_mov_b32_e32 v167, v51
	v_pk_fma_f32 v[166:167], v[166:167], v[166:167], v[196:197]
	v_mov_b32_e32 v196, v29
	s_waitcnt lgkmcnt(0)
; template <bool TO_BF16>
; DI void rms_rows(const int tid, const float* src, const float* gam, bf16_t* dst, float* fdst, int G, int c) {
;     ...
;         for (int o = 32; o > 0; o >>= 1)
; #pragma unroll
;             for (int q = 0; q < NR; ++q) s[q] += __shfl_xor(s[q], o);
; #pragma unroll
;         for (int q = 0; q < NR; ++q) { const float sc = rsqrtf(s[q] * (1.f / 1024.f) + 1e-6f);
; #pragma unroll
;             for (int k = 0; k < 4; ++k) {
;                 if (TO_BF16) { u32x2 o; o.x = pk2(v[q][k][0] * sc * g4[k][0], v[q][k][1] * sc * g4[k][1]); o.y = pk2(v[q][k][2] * sc * g4[k][2], v[q][k][3] * sc * g4[k][3]);
;                     *(u32x2*)(dst + (size_t)(r + q) * 1024 + k * 256 + lane * 4) = o; }
;                 else *(f32x4*)(fdst + (size_t)(r + q) * 1024 + k * 256 + lane * 4) = v[q][k] * sc * g4[k]; } }
	v_pk_add_f32 v[164:165], v[164:165], v[172:173]
	ds_bpermute_b32 v173, v183, v165
	ds_bpermute_b32 v172, v183, v164
	v_mov_b32_e32 v197, v25
	v_mov_b32_e32 v178, v28
	v_mov_b32_e32 v179, v24
	v_pk_mul_f32 v[196:197], v[196:197], v[196:197]
	s_waitcnt lgkmcnt(0)
	v_pk_add_f32 v[164:165], v[164:165], v[172:173]
	ds_bpermute_b32 v173, v192, v165
	ds_bpermute_b32 v172, v192, v164
	v_pk_fma_f32 v[178:179], v[178:179], v[178:179], v[196:197]
	v_mov_b32_e32 v196, v30
	v_mov_b32_e32 v197, v26
	v_pk_fma_f32 v[178:179], v[196:197], v[196:197], v[178:179]
	s_waitcnt lgkmcnt(0)
	v_pk_add_f32 v[164:165], v[164:165], v[172:173]
	ds_bpermute_b32 v197, v193, v165
	ds_bpermute_b32 v196, v193, v164
	v_mov_b32_e32 v172, v31
	v_mov_b32_e32 v173, v27
	v_mov_b32_e32 v198, v21
	v_mov_b32_e32 v199, v17
	s_waitcnt lgkmcnt(0)
	v_pk_add_f32 v[164:165], v[164:165], v[196:197]
	ds_bpermute_b32 v197, v194, v165
	ds_bpermute_b32 v196, v194, v164
	v_pk_fma_f32 v[172:173], v[172:173], v[172:173], v[178:179]
	v_mov_b32_e32 v178, v20
	v_mov_b32_e32 v179, v16
	v_pk_mul_f32 v[198:199], v[198:199], v[198:199]
	s_waitcnt lgkmcnt(0)
	v_pk_add_f32 v[164:165], v[164:165], v[196:197]
	ds_bpermute_b32 v197, v195, v165
	ds_bpermute_b32 v196, v195, v164
	v_pk_fma_f32 v[178:179], v[178:179], v[178:179], v[198:199]
	v_mov_b32_e32 v198, v22
	v_mov_b32_e32 v199, v18
	v_pk_fma_f32 v[178:179], v[198:199], v[198:199], v[178:179]
	s_waitcnt lgkmcnt(0)
	v_pk_add_f32 v[196:197], v[164:165], v[196:197]
	v_mov_b64_e32 v[164:165], s[14:15]
	v_pk_fma_f32 v[196:197], v[196:197], s[2:3], v[164:165] op_sel_hi:[1,0,0]
	v_mov_b32_e32 v198, v23
	v_mul_f32_e32 v145, 0x4b800000, v197
	v_cmp_gt_f32_e32 vcc, s3, v197
	v_mov_b32_e32 v199, v19
	v_pk_fma_f32 v[178:179], v[198:199], v[198:199], v[178:179]
	v_cndmask_b32_e32 v145, v197, v145, vcc
	v_rsq_f32_e32 v145, v145
	s_nop 0
	v_mul_f32_e32 v197, 0x45800000, v145
	v_cndmask_b32_e32 v198, v145, v197, vcc
	v_pk_mul_f32 v[132:133], v[132:133], v[198:199] op_sel_hi:[1,0]
	v_pk_mul_f32 v[134:135], v[134:135], v[198:199] op_sel_hi:[1,0]
	v_pk_mul_f32 v[132:133], v[8:9], v[132:133]
	v_pk_mul_f32 v[134:135], v[10:11], v[134:135]
	global_store_dwordx4 v[160:161], v[132:135], off offset:-1024
	v_pk_mul_f32 v[136:137], v[136:137], v[198:199] op_sel_hi:[1,0]
	v_pk_mul_f32 v[138:139], v[138:139], v[198:199] op_sel_hi:[1,0]
	v_mov_b32_e32 v132, v188
	v_mov_b32_e32 v133, v184
	v_mov_b32_e32 v184, v189
	v_pk_add_f32 v[132:133], v[132:133], v[184:185]
	v_mov_b32_e32 v134, v190
	v_mov_b32_e32 v135, v186
	v_pk_add_f32 v[132:133], v[132:133], v[134:135]
	v_mov_b32_e32 v186, v191
	v_pk_add_f32 v[132:133], v[132:133], v[186:187]
	ds_bpermute_b32 v135, v180, v133
	ds_bpermute_b32 v134, v180, v132
	v_pk_mul_f32 v[138:139], v[6:7], v[138:139]
	v_pk_mul_f32 v[136:137], v[4:5], v[136:137]
	global_store_dwordx4 v[160:161], v[136:139], off offset:-2048
	v_cmp_gt_f32_e32 vcc, s3, v196
	s_waitcnt lgkmcnt(0)
	v_pk_add_f32 v[132:133], v[132:133], v[134:135]
	ds_bpermute_b32 v135, v183, v133
	ds_bpermute_b32 v134, v183, v132
	v_mul_f32_e32 v136, 0x4b800000, v196
	v_cndmask_b32_e32 v136, v196, v136, vcc
	v_pk_mul_f32 v[128:129], v[128:129], v[198:199] op_sel_hi:[1,0]
	v_pk_mul_f32 v[130:131], v[130:131], v[198:199] op_sel_hi:[1,0]
	v_rsq_f32_e32 v136, v136
	v_pk_mul_f32 v[130:131], v[14:15], v[130:131]
	v_pk_mul_f32 v[128:129], v[12:13], v[128:129]
	global_store_dwordx4 v[160:161], v[128:131], off
	v_pk_mul_f32 v[140:141], v[140:141], v[198:199] op_sel_hi:[1,0]
	v_pk_mul_f32 v[142:143], v[142:143], v[198:199] op_sel_hi:[1,0]
	s_waitcnt lgkmcnt(0)
	v_pk_add_f32 v[130:131], v[132:133], v[134:135]
	ds_bpermute_b32 v133, v192, v131
	ds_bpermute_b32 v132, v192, v130
	v_mul_f32_e32 v128, 0x45800000, v136
	v_cndmask_b32_e32 v128, v136, v128, vcc
	v_pk_mul_f32 v[104:105], v[104:105], v[128:129] op_sel_hi:[1,0]
	v_pk_mul_f32 v[106:107], v[106:107], v[128:129] op_sel_hi:[1,0]
	v_pk_mul_f32 v[104:105], v[0:1], v[104:105]
	v_pk_mul_f32 v[106:107], v[2:3], v[106:107]
	global_store_dwordx4 v[158:159], v[104:107], off offset:-3072
	v_pk_mul_f32 v[96:97], v[96:97], v[128:129] op_sel_hi:[1,0]
	v_pk_mul_f32 v[98:99], v[98:99], v[128:129] op_sel_hi:[1,0]
	s_waitcnt lgkmcnt(0)
	v_pk_add_f32 v[104:105], v[130:131], v[132:133]
	ds_bpermute_b32 v107, v193, v105
	ds_bpermute_b32 v106, v193, v104
	v_pk_mul_f32 v[98:99], v[6:7], v[98:99]
	v_pk_mul_f32 v[96:97], v[4:5], v[96:97]
	global_store_dwordx4 v[158:159], v[96:99], off offset:-2048
	v_pk_mul_f32 v[142:143], v[2:3], v[142:143]
	s_waitcnt lgkmcnt(0)
	v_pk_add_f32 v[104:105], v[104:105], v[106:107]
	ds_bpermute_b32 v107, v194, v105
	ds_bpermute_b32 v106, v194, v104
	v_pk_mul_f32 v[96:97], v[124:125], v[128:129] op_sel_hi:[1,0]
	v_pk_mul_f32 v[98:99], v[126:127], v[128:129] op_sel_hi:[1,0]
	v_pk_mul_f32 v[96:97], v[8:9], v[96:97]
	v_pk_mul_f32 v[98:99], v[10:11], v[98:99]
	s_waitcnt lgkmcnt(0)
	v_pk_add_f32 v[104:105], v[104:105], v[106:107]
	ds_bpermute_b32 v107, v195, v105
	ds_bpermute_b32 v106, v195, v104
	global_store_dwordx4 v[158:159], v[96:99], off offset:-1024
	v_pk_mul_f32 v[140:141], v[0:1], v[140:141]
	global_store_dwordx4 v[160:161], v[140:143], off offset:-3072
	v_pk_mul_f32 v[96:97], v[120:121], v[128:129] op_sel_hi:[1,0]
	s_waitcnt lgkmcnt(0)
; template <bool TO_BF16>
; DI void rms_rows(const int tid, const float* src, const float* gam, bf16_t* dst, float* fdst, int G, int c) {
;     ...
;         for (int o = 32; o > 0; o >>= 1)
; #pragma unroll
;             for (int q = 0; q < NR; ++q) s[q] += __shfl_xor(s[q], o);
; #pragma unroll
;         for (int q = 0; q < NR; ++q) { const float sc = rsqrtf(s[q] * (1.f / 1024.f) + 1e-6f);
; #pragma unroll
;             for (int k = 0; k < 4; ++k) {
;                 if (TO_BF16) { u32x2 o; o.x = pk2(v[q][k][0] * sc * g4[k][0], v[q][k][1] * sc * g4[k][1]); o.y = pk2(v[q][k][2] * sc * g4[k][2], v[q][k][3] * sc * g4[k][3]);
;                     *(u32x2*)(dst + (size_t)(r + q) * 1024 + k * 256 + lane * 4) = o; }
;                 else *(f32x4*)(fdst + (size_t)(r + q) * 1024 + k * 256 + lane * 4) = v[q][k] * sc * g4[k]; } }
	v_pk_add_f32 v[104:105], v[104:105], v[106:107]
	v_pk_mul_f32 v[98:99], v[122:123], v[128:129] op_sel_hi:[1,0]
	v_pk_fma_f32 v[104:105], v[104:105], s[2:3], v[164:165] op_sel_hi:[1,0,0]
	v_pk_mul_f32 v[98:99], v[14:15], v[98:99]
	v_mul_f32_e32 v106, 0x4b800000, v105
	v_cmp_gt_f32_e32 vcc, s3, v105
	v_pk_mul_f32 v[96:97], v[12:13], v[96:97]
	global_store_dwordx4 v[158:159], v[96:99], off
	v_cndmask_b32_e32 v105, v105, v106, vcc
	v_rsq_f32_e32 v105, v105
	s_nop 0
	v_mul_f32_e32 v96, 0x45800000, v105
	v_cndmask_b32_e32 v106, v105, v96, vcc
	v_pk_mul_f32 v[96:97], v[116:117], v[106:107] op_sel_hi:[1,0]
	v_pk_mul_f32 v[98:99], v[118:119], v[106:107] op_sel_hi:[1,0]
	v_pk_mul_f32 v[96:97], v[0:1], v[96:97]
	v_pk_mul_f32 v[98:99], v[2:3], v[98:99]
	global_store_dwordx4 v[156:157], v[96:99], off offset:-3072
	v_mul_f32_e32 v105, 0x4b800000, v104
	v_cmp_gt_f32_e32 vcc, s3, v104
	v_pk_mul_f32 v[96:97], v[112:113], v[106:107] op_sel_hi:[1,0]
	v_pk_mul_f32 v[98:99], v[114:115], v[106:107] op_sel_hi:[1,0]
	v_pk_mul_f32 v[96:97], v[4:5], v[96:97]
	v_pk_mul_f32 v[98:99], v[6:7], v[98:99]
	global_store_dwordx4 v[156:157], v[96:99], off offset:-2048
	v_cndmask_b32_e32 v104, v104, v105, vcc
	v_rsq_f32_e32 v104, v104
	v_pk_mul_f32 v[96:97], v[108:109], v[106:107] op_sel_hi:[1,0]
	v_pk_mul_f32 v[98:99], v[110:111], v[106:107] op_sel_hi:[1,0]
	v_pk_mul_f32 v[96:97], v[8:9], v[96:97]
	v_pk_mul_f32 v[98:99], v[10:11], v[98:99]
	global_store_dwordx4 v[156:157], v[96:99], off offset:-1024
	s_nop 1
	v_pk_mul_f32 v[96:97], v[100:101], v[106:107] op_sel_hi:[1,0]
	v_mov_b32_e32 v100, v174
	v_mov_b32_e32 v101, v168
	v_mov_b32_e32 v168, v175
	v_pk_mul_f32 v[98:99], v[102:103], v[106:107] op_sel_hi:[1,0]
	v_pk_add_f32 v[100:101], v[100:101], v[168:169]
	v_mov_b32_e32 v102, v176
	v_mov_b32_e32 v103, v170
	v_pk_add_f32 v[100:101], v[100:101], v[102:103]
	v_mov_b32_e32 v170, v177
	v_pk_add_f32 v[100:101], v[100:101], v[170:171]
	ds_bpermute_b32 v103, v180, v101
	ds_bpermute_b32 v102, v180, v100
	v_pk_mul_f32 v[98:99], v[14:15], v[98:99]
	v_pk_mul_f32 v[96:97], v[12:13], v[96:97]
	global_store_dwordx4 v[156:157], v[96:99], off
	s_waitcnt lgkmcnt(0)
	v_pk_add_f32 v[100:101], v[100:101], v[102:103]
	ds_bpermute_b32 v103, v183, v101
	ds_bpermute_b32 v102, v183, v100
	v_mul_f32_e32 v96, 0x45800000, v104
	v_cndmask_b32_e32 v96, v104, v96, vcc
	v_pk_mul_f32 v[92:93], v[92:93], v[96:97] op_sel_hi:[1,0]
	v_pk_mul_f32 v[94:95], v[94:95], v[96:97] op_sel_hi:[1,0]
	s_waitcnt lgkmcnt(0)
	v_pk_add_f32 v[98:99], v[100:101], v[102:103]
	ds_bpermute_b32 v101, v192, v99
	ds_bpermute_b32 v100, v192, v98
	v_pk_mul_f32 v[94:95], v[2:3], v[94:95]
	v_pk_mul_f32 v[92:93], v[0:1], v[92:93]
	global_store_dwordx4 v[154:155], v[92:95], off offset:-3072
	v_pk_mul_f32 v[88:89], v[88:89], v[96:97] op_sel_hi:[1,0]
	v_pk_mul_f32 v[90:91], v[90:91], v[96:97] op_sel_hi:[1,0]
	s_waitcnt lgkmcnt(0)
	v_pk_add_f32 v[92:93], v[98:99], v[100:101]
	ds_bpermute_b32 v95, v193, v93
	ds_bpermute_b32 v94, v193, v92
	v_pk_mul_f32 v[90:91], v[6:7], v[90:91]
	v_pk_mul_f32 v[88:89], v[4:5], v[88:89]
	global_store_dwordx4 v[154:155], v[88:91], off offset:-2048
	v_pk_mul_f32 v[84:85], v[84:85], v[96:97] op_sel_hi:[1,0]
	s_waitcnt lgkmcnt(0)
	v_pk_add_f32 v[92:93], v[92:93], v[94:95]
	ds_bpermute_b32 v95, v194, v93
	ds_bpermute_b32 v94, v194, v92
	v_pk_mul_f32 v[86:87], v[86:87], v[96:97] op_sel_hi:[1,0]
	v_pk_mul_f32 v[84:85], v[8:9], v[84:85]
	v_pk_mul_f32 v[86:87], v[10:11], v[86:87]
	global_store_dwordx4 v[154:155], v[84:87], off offset:-1024
	s_waitcnt lgkmcnt(0)
	v_pk_add_f32 v[88:89], v[92:93], v[94:95]
	ds_bpermute_b32 v91, v195, v89
	ds_bpermute_b32 v90, v195, v88
	v_pk_mul_f32 v[80:81], v[80:81], v[96:97] op_sel_hi:[1,0]
	v_pk_mul_f32 v[82:83], v[82:83], v[96:97] op_sel_hi:[1,0]
	v_pk_mul_f32 v[80:81], v[12:13], v[80:81]
	v_pk_mul_f32 v[82:83], v[14:15], v[82:83]
	s_waitcnt lgkmcnt(0)
	v_pk_add_f32 v[84:85], v[88:89], v[90:91]
	global_store_dwordx4 v[154:155], v[80:83], off
	v_pk_fma_f32 v[84:85], v[84:85], s[2:3], v[164:165] op_sel_hi:[1,0,0]
	s_nop 0
	v_mul_f32_e32 v86, 0x4b800000, v85
	v_cmp_gt_f32_e32 vcc, s3, v85
	s_nop 1
	v_cndmask_b32_e32 v85, v85, v86, vcc
	v_rsq_f32_e32 v85, v85
	s_nop 0
	v_mul_f32_e32 v80, 0x45800000, v85
	v_cndmask_b32_e32 v80, v85, v80, vcc
	v_pk_mul_f32 v[68:69], v[68:69], v[80:81] op_sel_hi:[1,0]
	v_pk_mul_f32 v[70:71], v[70:71], v[80:81] op_sel_hi:[1,0]
	v_pk_mul_f32 v[68:69], v[8:9], v[68:69]
	v_pk_mul_f32 v[70:71], v[10:11], v[70:71]
	global_store_dwordx4 v[152:153], v[68:71], off offset:-1024
	v_pk_mul_f32 v[72:73], v[72:73], v[80:81] op_sel_hi:[1,0]
	v_pk_mul_f32 v[74:75], v[74:75], v[80:81] op_sel_hi:[1,0]
	v_mov_b32_e32 v68, v172
	v_mov_b32_e32 v69, v162
	v_mov_b32_e32 v162, v173
	v_pk_add_f32 v[68:69], v[68:69], v[162:163]
	v_mov_b32_e32 v70, v178
	v_mov_b32_e32 v71, v166
	v_pk_add_f32 v[68:69], v[68:69], v[70:71]
	v_mov_b32_e32 v166, v179
	v_pk_add_f32 v[68:69], v[68:69], v[166:167]
	ds_bpermute_b32 v71, v180, v69
	ds_bpermute_b32 v70, v180, v68
	v_pk_mul_f32 v[74:75], v[6:7], v[74:75]
	v_pk_mul_f32 v[72:73], v[4:5], v[72:73]
	global_store_dwordx4 v[152:153], v[72:75], off offset:-2048
	v_cmp_gt_f32_e32 vcc, s3, v84
	s_waitcnt lgkmcnt(0)
; template <bool TO_BF16>
; DI void rms_rows(const int tid, const float* src, const float* gam, bf16_t* dst, float* fdst, int G, int c) {
;     ...
;     for (int r = (c * 8 + wave) * NR; r < MTOK; r += G * 8 * NR) {
;         f32x4 v[NR][4]; float s[NR];
; #pragma unroll
;         for (int q = 0; q < NR; ++q)
; #pragma unroll
;             for (int k = 0; k < 4; ++k) v[q][k] = *(const f32x4*)(src + (size_t)(r + q) * 1024 + k * 256 + lane * 4);
; #pragma unroll
;         for (int q = 0; q < NR; ++q) { s[q] = 0.f;
; #pragma unroll
;             for (int k = 0; k < 4; ++k) s[q] += v[q][k][0] * v[q][k][0] + v[q][k][1] * v[q][k][1] + v[q][k][2] * v[q][k][2] + v[q][k][3] * v[q][k][3]; }
; #pragma unroll
;         for (int o = 32; o > 0; o >>= 1)
; #pragma unroll
;             for (int q = 0; q < NR; ++q) s[q] += __shfl_xor(s[q], o);
; #pragma unroll
;         for (int q = 0; q < NR; ++q) { const float sc = rsqrtf(s[q] * (1.f / 1024.f) + 1e-6f);
; #pragma unroll
;             for (int k = 0; k < 4; ++k) {
;                 if (TO_BF16) { u32x2 o; o.x = pk2(v[q][k][0] * sc * g4[k][0], v[q][k][1] * sc * g4[k][1]); o.y = pk2(v[q][k][2] * sc * g4[k][2], v[q][k][3] * sc * g4[k][3]);
;                     *(u32x2*)(dst + (size_t)(r + q) * 1024 + k * 256 + lane * 4) = o; }
;                 else *(f32x4*)(fdst + (size_t)(r + q) * 1024 + k * 256 + lane * 4) = v[q][k] * sc * g4[k]; } }
	v_pk_add_f32 v[68:69], v[68:69], v[70:71]
	ds_bpermute_b32 v71, v183, v69
	ds_bpermute_b32 v70, v183, v68
	v_mul_f32_e32 v72, 0x4b800000, v84
	v_cndmask_b32_e32 v72, v84, v72, vcc
	v_pk_mul_f32 v[64:65], v[64:65], v[80:81] op_sel_hi:[1,0]
	v_pk_mul_f32 v[66:67], v[66:67], v[80:81] op_sel_hi:[1,0]
	v_rsq_f32_e32 v72, v72
	v_pk_mul_f32 v[66:67], v[14:15], v[66:67]
	v_pk_mul_f32 v[64:65], v[12:13], v[64:65]
	global_store_dwordx4 v[152:153], v[64:67], off
	v_pk_mul_f32 v[76:77], v[76:77], v[80:81] op_sel_hi:[1,0]
	v_pk_mul_f32 v[78:79], v[78:79], v[80:81] op_sel_hi:[1,0]
	s_waitcnt lgkmcnt(0)
	v_pk_add_f32 v[66:67], v[68:69], v[70:71]
	ds_bpermute_b32 v69, v192, v67
	ds_bpermute_b32 v68, v192, v66
	v_mul_f32_e32 v64, 0x45800000, v72
	v_cndmask_b32_e32 v64, v72, v64, vcc
	v_pk_mul_f32 v[60:61], v[60:61], v[64:65] op_sel_hi:[1,0]
	v_pk_mul_f32 v[62:63], v[62:63], v[64:65] op_sel_hi:[1,0]
	v_pk_mul_f32 v[60:61], v[0:1], v[60:61]
	v_pk_mul_f32 v[62:63], v[2:3], v[62:63]
	global_store_dwordx4 v[150:151], v[60:63], off offset:-3072
	v_pk_mul_f32 v[56:57], v[56:57], v[64:65] op_sel_hi:[1,0]
	v_pk_mul_f32 v[58:59], v[58:59], v[64:65] op_sel_hi:[1,0]
	s_waitcnt lgkmcnt(0)
	v_pk_add_f32 v[60:61], v[66:67], v[68:69]
	ds_bpermute_b32 v63, v193, v61
	ds_bpermute_b32 v62, v193, v60
	v_pk_mul_f32 v[58:59], v[6:7], v[58:59]
	v_pk_mul_f32 v[56:57], v[4:5], v[56:57]
	global_store_dwordx4 v[150:151], v[56:59], off offset:-2048
	v_pk_mul_f32 v[52:53], v[52:53], v[64:65] op_sel_hi:[1,0]
	s_waitcnt lgkmcnt(0)
	v_pk_add_f32 v[60:61], v[60:61], v[62:63]
	ds_bpermute_b32 v63, v194, v61
	ds_bpermute_b32 v62, v194, v60
	v_pk_mul_f32 v[54:55], v[54:55], v[64:65] op_sel_hi:[1,0]
	v_pk_mul_f32 v[52:53], v[8:9], v[52:53]
	v_pk_mul_f32 v[54:55], v[10:11], v[54:55]
	global_store_dwordx4 v[150:151], v[52:55], off offset:-1024
	s_waitcnt lgkmcnt(0)
	v_pk_add_f32 v[56:57], v[60:61], v[62:63]
	ds_bpermute_b32 v59, v195, v57
	ds_bpermute_b32 v58, v195, v56
	v_pk_mul_f32 v[44:45], v[44:45], v[64:65] op_sel_hi:[1,0]
	v_pk_mul_f32 v[46:47], v[46:47], v[64:65] op_sel_hi:[1,0]
	v_pk_mul_f32 v[44:45], v[12:13], v[44:45]
	v_pk_mul_f32 v[46:47], v[14:15], v[46:47]
	s_waitcnt lgkmcnt(0)
	v_pk_add_f32 v[52:53], v[56:57], v[58:59]
	global_store_dwordx4 v[150:151], v[44:47], off
	v_pk_fma_f32 v[52:53], v[52:53], s[2:3], v[164:165] op_sel_hi:[1,0,0]
	v_pk_mul_f32 v[78:79], v[2:3], v[78:79]
	v_mul_f32_e32 v54, 0x4b800000, v53
	v_cmp_gt_f32_e32 vcc, s3, v53
	v_pk_mul_f32 v[76:77], v[0:1], v[76:77]
	global_store_dwordx4 v[152:153], v[76:79], off offset:-3072
	v_cndmask_b32_e32 v53, v53, v54, vcc
	v_rsq_f32_e32 v53, v53
	s_nop 0
	v_mul_f32_e32 v44, 0x45800000, v53
	v_cndmask_b32_e32 v44, v53, v44, vcc
	v_pk_mul_f32 v[36:37], v[36:37], v[44:45] op_sel_hi:[1,0]
	v_pk_mul_f32 v[38:39], v[38:39], v[44:45] op_sel_hi:[1,0]
	v_pk_mul_f32 v[36:37], v[4:5], v[36:37]
	v_pk_mul_f32 v[38:39], v[6:7], v[38:39]
	global_store_dwordx4 v[148:149], v[36:39], off offset:-2048
	v_cmp_gt_f32_e32 vcc, s3, v52
	v_pk_mul_f32 v[32:33], v[32:33], v[44:45] op_sel_hi:[1,0]
	v_mul_f32_e32 v36, 0x4b800000, v52
	v_cndmask_b32_e32 v36, v52, v36, vcc
	v_pk_mul_f32 v[34:35], v[34:35], v[44:45] op_sel_hi:[1,0]
	v_rsq_f32_e32 v36, v36
	v_pk_mul_f32 v[34:35], v[10:11], v[34:35]
	v_pk_mul_f32 v[32:33], v[8:9], v[32:33]
	global_store_dwordx4 v[148:149], v[32:35], off offset:-1024
	v_pk_mul_f32 v[40:41], v[40:41], v[44:45] op_sel_hi:[1,0]
	v_pk_mul_f32 v[42:43], v[42:43], v[44:45] op_sel_hi:[1,0]
	v_pk_mul_f32 v[32:33], v[48:49], v[44:45] op_sel_hi:[1,0]
	v_pk_mul_f32 v[34:35], v[50:51], v[44:45] op_sel_hi:[1,0]
	v_pk_mul_f32 v[32:33], v[12:13], v[32:33]
	v_pk_mul_f32 v[34:35], v[14:15], v[34:35]
	global_store_dwordx4 v[146:147], v[32:35], off offset:-4096
	v_pk_mul_f32 v[42:43], v[2:3], v[42:43]
	v_pk_mul_f32 v[40:41], v[0:1], v[40:41]
	v_mul_f32_e32 v32, 0x45800000, v36
	v_cndmask_b32_e32 v32, v36, v32, vcc
	v_pk_mul_f32 v[28:29], v[28:29], v[32:33] op_sel_hi:[1,0]
	v_pk_mul_f32 v[30:31], v[30:31], v[32:33] op_sel_hi:[1,0]
	v_pk_mul_f32 v[24:25], v[24:25], v[32:33] op_sel_hi:[1,0]
	v_pk_mul_f32 v[26:27], v[26:27], v[32:33] op_sel_hi:[1,0]
	v_pk_mul_f32 v[20:21], v[20:21], v[32:33] op_sel_hi:[1,0]
	v_pk_mul_f32 v[22:23], v[22:23], v[32:33] op_sel_hi:[1,0]
	v_pk_mul_f32 v[16:17], v[16:17], v[32:33] op_sel_hi:[1,0]
	v_pk_mul_f32 v[18:19], v[18:19], v[32:33] op_sel_hi:[1,0]
	v_pk_mul_f32 v[30:31], v[2:3], v[30:31]
	v_pk_mul_f32 v[28:29], v[0:1], v[28:29]
	v_pk_mul_f32 v[26:27], v[6:7], v[26:27]
	v_pk_mul_f32 v[24:25], v[4:5], v[24:25]
	v_pk_mul_f32 v[22:23], v[10:11], v[22:23]
	v_pk_mul_f32 v[20:21], v[8:9], v[20:21]
	v_pk_mul_f32 v[18:19], v[14:15], v[18:19]
	v_pk_mul_f32 v[16:17], v[12:13], v[16:17]
	v_cmp_lt_i32_e32 vcc, s70, v144
	global_store_dwordx4 v[146:147], v[28:31], off offset:-3072
	global_store_dwordx4 v[146:147], v[24:27], off offset:-2048
	global_store_dwordx4 v[146:147], v[20:23], off offset:-1024
	global_store_dwordx4 v[146:147], v[16:19], off
	s_or_b64 s[4:5], vcc, s[4:5]
	v_bfe_u32 v146, v144, 11, 3
	v_lshrrev_b32_e32 v147, 14, v144
	v_sub_u32_e32 v147, 3, v147
	v_lshlrev_b32_e32 v147, 11, v147
	v_lshl_or_b32 v146, v146, 13, v147
	v_and_b32_e32 v147, 0x7ff, v144
	v_or_b32_e32 v146, v146, v147
	v_lshlrev_b32_e32 v146, 12, v146
	v_and_b32_e32 v147, 63, v182
	v_lshl_or_b32 v146, v147, 4, v146
	v_mov_b32_e32 v147, 0
	v_lshl_add_u64 v[146:147], s[98:99], 0, v[146:147]
	global_store_dwordx4 v[148:149], v[40:43], off offset:-3072
	s_andn2_b64 exec, exec, s[4:5]
	s_cbranch_execnz .LBB0_76

; template <bool TO_BF16>
; DI void rms_rows(const int tid, const float* src, const float* gam, bf16_t* dst, float* fdst, int G, int c) {
;     ...
;     const int wave = tid >> 6, lane = tid & 63;
;     f32x4 g4[4];
; #pragma unroll
;     for (int k = 0; k < 4; ++k) g4[k] = *(const f32x4*)(gam + k * 256 + lane * 4);
;     for (int r = (c * 8 + wave) * NR; r < MTOK; r += G * 8 * NR) {
;         f32x4 v[NR][4]; float s[NR];
; #pragma unroll
;         for (int q = 0; q < NR; ++q)
; #pragma unroll
;             for (int k = 0; k < 4; ++k) v[q][k] = *(const f32x4*)(src + (size_t)(r + q) * 1024 + k * 256 + lane * 4);
.LBB0_391:
	s_andn2_b64 vcc, exec, s[0:1]
	s_cbranch_vccnz .LBB0_396
	v_ashrrev_i32_e32 v0, 3, v182
	v_and_b32_e32 v0, -8, v0
	v_readlane_b32 s0, v250, 0
	s_nop 1
	v_add_u32_e32 v144, s0, v0
	s_mov_b32 s0, 0x10000
	v_cmp_gt_i32_e32 vcc, s0, v144
	s_and_saveexec_b64 s[4:5], vcc
	s_cbranch_execz .LBB0_395
	v_lshlrev_b32_e32 v0, 4, v182
	v_readlane_b32 s0, v250, 43
	v_and_b32_e32 v12, 0x3f0, v0
	v_readlane_b32 s1, v250, 44
	s_nop 4
	global_load_dwordx4 v[0:3], v12, s[0:1] offset:3072
	global_load_dwordx4 v[4:7], v12, s[0:1] offset:2048
	global_load_dwordx4 v[8:11], v12, s[0:1] offset:1024
	s_nop 0
	global_load_dwordx4 v[12:15], v12, s[0:1]
	v_and_b32_e32 v16, 64, v234
	v_add_u32_e32 v16, 64, v16
	v_xor_b32_e32 v17, 32, v234
	v_cmp_lt_i32_e32 vcc, v17, v16
	v_ashrrev_i32_e32 v145, 31, v144
	v_and_b32_e32 v18, 63, v182
	v_cndmask_b32_e32 v17, v234, v17, vcc
	v_lshlrev_b32_e32 v178, 2, v17
	v_xor_b32_e32 v17, 16, v234
	v_cmp_lt_i32_e32 vcc, v17, v16
	v_readlane_b32 s0, v253, 8
	v_readlane_b32 s1, v253, 9
	v_cndmask_b32_e32 v17, v234, v17, vcc
	v_lshlrev_b32_e32 v179, 2, v17
	v_xor_b32_e32 v17, 8, v234
	v_cmp_lt_i32_e32 vcc, v17, v16
	s_mov_b64 s[6:7], 0
	s_nop 0
	v_cndmask_b32_e32 v17, v234, v17, vcc
	v_lshlrev_b32_e32 v180, 2, v17
	v_xor_b32_e32 v17, 4, v234
	v_cmp_lt_i32_e32 vcc, v17, v16
	s_nop 1
	v_cndmask_b32_e32 v17, v234, v17, vcc
	v_lshlrev_b32_e32 v183, 2, v17
	v_xor_b32_e32 v17, 2, v234
	v_cmp_lt_i32_e32 vcc, v17, v16
	s_nop 1
	v_cndmask_b32_e32 v17, v234, v17, vcc
	v_lshlrev_b32_e32 v184, 2, v17
	v_xor_b32_e32 v17, 1, v234
	v_cmp_lt_i32_e32 vcc, v17, v16
	s_nop 1
	v_cndmask_b32_e32 v16, v234, v17, vcc
	v_lshlrev_b32_e32 v185, 2, v16
	v_lshlrev_b64 v[16:17], 11, v[144:145]
	v_lshl_or_b32 v16, v18, 3, v16
	v_lshl_add_u64 v[146:147], s[0:1], 0, v[16:17]
	v_lshlrev_b64 v[16:17], 12, v[144:145]
	v_readlane_b32 s0, v253, 4
	v_lshl_or_b32 v16, v18, 4, v16
	v_readlane_b32 s1, v253, 5
	s_nop 1
	v_lshl_add_u64 v[148:149], s[0:1], 0, v[16:17]
	v_readlane_b32 s98, v253, 4
	v_readlane_b32 s99, v253, 5
	v_readlane_b32 s100, v253, 8
	v_readlane_b32 s101, v253, 9
	s_nop 3
	v_bfe_u32 v148, v144, 11, 3
	v_lshrrev_b32_e32 v149, 14, v144
	v_sub_u32_e32 v149, 3, v149
	v_lshlrev_b32_e32 v149, 11, v149
	v_lshl_or_b32 v148, v148, 13, v149
	v_and_b32_e32 v149, 0x7ff, v144
	v_or_b32_e32 v148, v148, v149
	v_lshlrev_b32_e32 v148, 12, v148
	v_and_b32_e32 v149, 63, v182
	v_lshl_or_b32 v148, v149, 4, v148
	v_mov_b32_e32 v149, 0
	v_lshl_add_u64 v[148:149], s[98:99], 0, v[148:149]
	v_bfe_u32 v146, v144, 11, 3
	v_lshrrev_b32_e32 v147, 14, v144
	v_sub_u32_e32 v147, 3, v147
	v_lshlrev_b32_e32 v147, 11, v147
	v_lshl_or_b32 v146, v146, 13, v147
	v_and_b32_e32 v147, 0x7ff, v144
	v_or_b32_e32 v146, v146, v147
	v_lshlrev_b32_e32 v146, 11, v146
	v_and_b32_e32 v147, 63, v182
	v_lshl_or_b32 v146, v147, 3, v146
	v_mov_b32_e32 v147, 0
	v_lshl_add_u64 v[146:147], s[100:101], 0, v[146:147]
.LBB0_394:
	v_add_co_u32_e32 v16, vcc, 0xffff9000, v148
	v_add_u32_e32 v144, s66, v144
	s_nop 0
	v_addc_co_u32_e32 v17, vcc, -1, v149, vcc
	global_load_dwordx4 v[140:143], v[16:17], off offset:-3072
	global_load_dwordx4 v[136:139], v[16:17], off offset:-2048
	global_load_dwordx4 v[132:135], v[16:17], off offset:-1024
	global_load_dwordx4 v[128:131], v[16:17], off
	v_add_co_u32_e32 v16, vcc, 0xffffa000, v148
	s_waitcnt vmcnt(0)
	v_mov_b32_e32 v152, v141
	v_addc_co_u32_e32 v17, vcc, -1, v149, vcc
	global_load_dwordx4 v[124:127], v[16:17], off offset:-3072
	global_load_dwordx4 v[120:123], v[16:17], off offset:-2048
	global_load_dwordx4 v[116:119], v[16:17], off offset:-1024
	global_load_dwordx4 v[112:115], v[16:17], off
	v_add_co_u32_e32 v16, vcc, 0xffffb000, v148
	s_waitcnt vmcnt(6)
	v_mov_b32_e32 v153, v137
	v_addc_co_u32_e32 v17, vcc, -1, v149, vcc
	global_load_dwordx4 v[108:111], v[16:17], off offset:-3072
	global_load_dwordx4 v[104:107], v[16:17], off offset:-2048
	global_load_dwordx4 v[100:103], v[16:17], off offset:-1024
	global_load_dwordx4 v[96:99], v[16:17], off
	v_add_co_u32_e32 v16, vcc, 0xffffc000, v148
	v_mov_b32_e32 v150, v140
	s_nop 0
	v_addc_co_u32_e32 v17, vcc, -1, v149, vcc
	global_load_dwordx4 v[92:95], v[16:17], off offset:-3072
	global_load_dwordx4 v[88:91], v[16:17], off offset:-2048
	global_load_dwordx4 v[84:87], v[16:17], off offset:-1024
	global_load_dwordx4 v[80:83], v[16:17], off
	v_add_co_u32_e32 v16, vcc, 0xffffd000, v148
	v_mov_b32_e32 v151, v136
	s_nop 0
	v_addc_co_u32_e32 v17, vcc, -1, v149, vcc
	global_load_dwordx4 v[76:79], v[16:17], off offset:-3072
	global_load_dwordx4 v[56:59], v[16:17], off offset:-2048
	global_load_dwordx4 v[52:55], v[16:17], off offset:-1024
	global_load_dwordx4 v[48:51], v[16:17], off
	v_add_co_u32_e32 v16, vcc, 0xffffe000, v148
	v_pk_mul_f32 v[152:153], v[152:153], v[152:153]
	s_nop 0
	v_addc_co_u32_e32 v17, vcc, -1, v149, vcc
	global_load_dwordx4 v[44:47], v[16:17], off offset:-3072
	global_load_dwordx4 v[40:43], v[16:17], off offset:-2048
	global_load_dwordx4 v[36:39], v[16:17], off offset:-1024
	global_load_dwordx4 v[32:35], v[16:17], off
	v_add_co_u32_e32 v16, vcc, 0xfffff000, v148
	v_pk_fma_f32 v[150:151], v[150:151], v[150:151], v[152:153]
	s_nop 0
	v_addc_co_u32_e32 v17, vcc, -1, v149, vcc
	global_load_dwordx4 v[28:31], v[16:17], off offset:-3072
	global_load_dwordx4 v[24:27], v[16:17], off offset:-2048
	global_load_dwordx4 v[20:23], v[16:17], off offset:-1024
	s_nop 0
	global_load_dwordx4 v[16:19], v[148:149], off offset:-4096
	global_load_dwordx4 v[72:75], v[148:149], off offset:-3072
	global_load_dwordx4 v[68:71], v[148:149], off offset:-2048
	global_load_dwordx4 v[64:67], v[148:149], off offset:-1024
	global_load_dwordx4 v[60:63], v[148:149], off
	v_mov_b32_e32 v152, v142
	v_mov_b32_e32 v153, v138
	v_pk_fma_f32 v[150:151], v[152:153], v[152:153], v[150:151]
	v_mov_b32_e32 v152, v143
	v_mov_b32_e32 v153, v139
	v_pk_fma_f32 v[174:175], v[152:153], v[152:153], v[150:151]
	s_waitcnt vmcnt(29)
; template <bool TO_BF16>
; DI void rms_rows(const int tid, const float* src, const float* gam, bf16_t* dst, float* fdst, int G, int c) {
;     ...
;             for (int k = 0; k < 4; ++k) v[q][k] = *(const f32x4*)(src + (size_t)(r + q) * 1024 + k * 256 + lane * 4);
; #pragma unroll
;         for (int q = 0; q < NR; ++q) { s[q] = 0.f;
; #pragma unroll
;             for (int k = 0; k < 4; ++k) s[q] += v[q][k][0] * v[q][k][0] + v[q][k][1] * v[q][k][1] + v[q][k][2] * v[q][k][2] + v[q][k][3] * v[q][k][3]; }
	v_mov_b32_e32 v152, v133
	s_waitcnt vmcnt(28)
	v_mov_b32_e32 v153, v129
	v_mov_b32_e32 v150, v132
	v_mov_b32_e32 v151, v128
	v_pk_mul_f32 v[152:153], v[152:153], v[152:153]
	v_bfe_u32 v148, v144, 11, 3
	v_lshrrev_b32_e32 v149, 14, v144
	v_sub_u32_e32 v149, 3, v149
	v_lshlrev_b32_e32 v149, 11, v149
	v_lshl_or_b32 v148, v148, 13, v149
	v_and_b32_e32 v149, 0x7ff, v144
	v_or_b32_e32 v148, v148, v149
	v_lshlrev_b32_e32 v148, 12, v148
	v_and_b32_e32 v149, 63, v182
	v_lshl_or_b32 v148, v149, 4, v148
	v_mov_b32_e32 v149, 0
	v_lshl_add_u64 v[148:149], s[98:99], 0, v[148:149]
	v_pk_fma_f32 v[150:151], v[150:151], v[150:151], v[152:153]
	v_mov_b32_e32 v152, v134
	v_mov_b32_e32 v153, v130
	v_pk_fma_f32 v[150:151], v[152:153], v[152:153], v[150:151]
	v_mov_b32_e32 v152, v135
	v_mov_b32_e32 v153, v131
	v_pk_fma_f32 v[176:177], v[152:153], v[152:153], v[150:151]
	s_waitcnt vmcnt(0)
	v_mov_b32_e32 v152, v125
	s_waitcnt vmcnt(26)
	v_mov_b32_e32 v153, v121
	v_mov_b32_e32 v150, v124
	v_mov_b32_e32 v151, v120
	v_pk_mul_f32 v[152:153], v[152:153], v[152:153]
	s_waitcnt vmcnt(5)
	v_mov_b32_e32 v154, v21
	v_pk_fma_f32 v[150:151], v[150:151], v[150:151], v[152:153]
	v_mov_b32_e32 v152, v126
	v_mov_b32_e32 v153, v122
	v_pk_fma_f32 v[150:151], v[152:153], v[152:153], v[150:151]
	v_mov_b32_e32 v152, v127
	v_mov_b32_e32 v153, v123
	v_pk_fma_f32 v[186:187], v[152:153], v[152:153], v[150:151]
	v_mov_b32_e32 v152, v117
	v_mov_b32_e32 v153, v113
	v_mov_b32_e32 v150, v116
	v_mov_b32_e32 v151, v112
	v_pk_mul_f32 v[152:153], v[152:153], v[152:153]
	s_waitcnt vmcnt(4)
	v_mov_b32_e32 v155, v17
	v_pk_fma_f32 v[150:151], v[150:151], v[150:151], v[152:153]
	v_mov_b32_e32 v152, v118
	v_mov_b32_e32 v153, v114
	v_pk_fma_f32 v[150:151], v[152:153], v[152:153], v[150:151]
	v_mov_b32_e32 v152, v119
	v_mov_b32_e32 v153, v115
	v_pk_fma_f32 v[188:189], v[152:153], v[152:153], v[150:151]
	v_mov_b32_e32 v152, v109
	v_mov_b32_e32 v153, v105
	v_mov_b32_e32 v150, v108
	v_mov_b32_e32 v151, v104
	v_pk_mul_f32 v[152:153], v[152:153], v[152:153]
	v_pk_mul_f32 v[154:155], v[154:155], v[154:155]
	v_pk_fma_f32 v[150:151], v[150:151], v[150:151], v[152:153]
	v_mov_b32_e32 v152, v110
	v_mov_b32_e32 v153, v106
	v_pk_fma_f32 v[150:151], v[152:153], v[152:153], v[150:151]
	v_mov_b32_e32 v152, v111
	v_mov_b32_e32 v153, v107
	v_pk_fma_f32 v[166:167], v[152:153], v[152:153], v[150:151]
	v_mov_b32_e32 v152, v101
	v_mov_b32_e32 v153, v97
	v_mov_b32_e32 v150, v100
	v_mov_b32_e32 v151, v96
	v_pk_mul_f32 v[152:153], v[152:153], v[152:153]
	s_waitcnt vmcnt(3)
	v_mov_b32_e32 v156, v73
	v_pk_fma_f32 v[150:151], v[150:151], v[150:151], v[152:153]
	v_mov_b32_e32 v152, v102
	v_mov_b32_e32 v153, v98
	v_pk_fma_f32 v[150:151], v[152:153], v[152:153], v[150:151]
	v_mov_b32_e32 v152, v103
	v_mov_b32_e32 v153, v99
	v_pk_fma_f32 v[168:169], v[152:153], v[152:153], v[150:151]
	v_mov_b32_e32 v152, v93
	v_mov_b32_e32 v153, v89
	v_mov_b32_e32 v150, v92
	v_mov_b32_e32 v151, v88
	v_pk_mul_f32 v[152:153], v[152:153], v[152:153]
	s_waitcnt vmcnt(2)
	v_mov_b32_e32 v157, v69
	v_pk_fma_f32 v[150:151], v[150:151], v[150:151], v[152:153]
	v_mov_b32_e32 v152, v94
	v_mov_b32_e32 v153, v90
	v_pk_fma_f32 v[150:151], v[152:153], v[152:153], v[150:151]
	v_mov_b32_e32 v152, v95
	v_mov_b32_e32 v153, v91
	v_pk_fma_f32 v[170:171], v[152:153], v[152:153], v[150:151]
	v_mov_b32_e32 v152, v85
	v_mov_b32_e32 v153, v81
	v_mov_b32_e32 v150, v84
	v_mov_b32_e32 v151, v80
	v_pk_mul_f32 v[152:153], v[152:153], v[152:153]
	v_pk_mul_f32 v[156:157], v[156:157], v[156:157]
	v_pk_fma_f32 v[150:151], v[150:151], v[150:151], v[152:153]
	v_mov_b32_e32 v152, v86
	v_mov_b32_e32 v153, v82
	v_pk_fma_f32 v[150:151], v[152:153], v[152:153], v[150:151]
	v_mov_b32_e32 v152, v87
	v_mov_b32_e32 v153, v83
	v_pk_fma_f32 v[172:173], v[152:153], v[152:153], v[150:151]
	v_mov_b32_e32 v152, v77
	v_mov_b32_e32 v153, v57
	v_mov_b32_e32 v150, v76
	v_mov_b32_e32 v151, v56
	v_pk_mul_f32 v[152:153], v[152:153], v[152:153]
	s_waitcnt vmcnt(1)
	v_mov_b32_e32 v190, v65
	v_pk_fma_f32 v[150:151], v[150:151], v[150:151], v[152:153]
	v_mov_b32_e32 v152, v78
	v_mov_b32_e32 v153, v58
	v_pk_fma_f32 v[150:151], v[152:153], v[152:153], v[150:151]
	v_mov_b32_e32 v152, v79
	v_mov_b32_e32 v153, v59
	v_pk_fma_f32 v[158:159], v[152:153], v[152:153], v[150:151]
	v_mov_b32_e32 v152, v53
	v_mov_b32_e32 v153, v49
	v_mov_b32_e32 v150, v52
	v_mov_b32_e32 v151, v48
	v_pk_mul_f32 v[152:153], v[152:153], v[152:153]
	s_waitcnt vmcnt(0)
; template <bool TO_BF16>
; DI void rms_rows(const int tid, const float* src, const float* gam, bf16_t* dst, float* fdst, int G, int c) {
;     ...
;         for (int q = 0; q < NR; ++q) { s[q] = 0.f;
; #pragma unroll
;             for (int k = 0; k < 4; ++k) s[q] += v[q][k][0] * v[q][k][0] + v[q][k][1] * v[q][k][1] + v[q][k][2] * v[q][k][2] + v[q][k][3] * v[q][k][3]; }
; #pragma unroll
;         for (int o = 32; o > 0; o >>= 1)
; #pragma unroll
;             for (int q = 0; q < NR; ++q) s[q] += __shfl_xor(s[q], o);
; #pragma unroll
;         for (int q = 0; q < NR; ++q) { const float sc = rsqrtf(s[q] * (1.f / 1024.f) + 1e-6f);
; #pragma unroll
;             for (int k = 0; k < 4; ++k) {
;                 if (TO_BF16) { u32x2 o; o.x = pk2(v[q][k][0] * sc * g4[k][0], v[q][k][1] * sc * g4[k][1]); o.y = pk2(v[q][k][2] * sc * g4[k][2], v[q][k][3] * sc * g4[k][3]);
	v_mov_b32_e32 v191, v61
	v_pk_fma_f32 v[150:151], v[150:151], v[150:151], v[152:153]
	v_mov_b32_e32 v152, v54
	v_mov_b32_e32 v153, v50
	v_pk_fma_f32 v[150:151], v[152:153], v[152:153], v[150:151]
	v_mov_b32_e32 v152, v55
	v_mov_b32_e32 v153, v51
	v_pk_fma_f32 v[160:161], v[152:153], v[152:153], v[150:151]
	v_mov_b32_e32 v152, v45
	v_mov_b32_e32 v153, v41
	v_mov_b32_e32 v150, v44
	v_mov_b32_e32 v151, v40
	v_pk_mul_f32 v[152:153], v[152:153], v[152:153]
	v_pk_mul_f32 v[190:191], v[190:191], v[190:191]
	v_pk_fma_f32 v[150:151], v[150:151], v[150:151], v[152:153]
	v_mov_b32_e32 v152, v46
	v_mov_b32_e32 v153, v42
	v_pk_fma_f32 v[150:151], v[152:153], v[152:153], v[150:151]
	v_mov_b32_e32 v152, v47
	v_mov_b32_e32 v153, v43
	v_pk_fma_f32 v[162:163], v[152:153], v[152:153], v[150:151]
	v_mov_b32_e32 v152, v37
	v_mov_b32_e32 v153, v33
	v_mov_b32_e32 v150, v36
	v_mov_b32_e32 v151, v32
	v_pk_mul_f32 v[152:153], v[152:153], v[152:153]
	s_nop 0
	v_pk_fma_f32 v[150:151], v[150:151], v[150:151], v[152:153]
	v_mov_b32_e32 v152, v38
	v_mov_b32_e32 v153, v34
	v_pk_fma_f32 v[150:151], v[152:153], v[152:153], v[150:151]
	v_mov_b32_e32 v152, v39
	v_mov_b32_e32 v153, v35
	v_pk_fma_f32 v[164:165], v[152:153], v[152:153], v[150:151]
	v_mov_b32_e32 v152, v29
	v_mov_b32_e32 v153, v25
	v_mov_b32_e32 v150, v28
	v_mov_b32_e32 v151, v24
	v_pk_mul_f32 v[152:153], v[152:153], v[152:153]
	s_nop 0
	v_pk_fma_f32 v[150:151], v[150:151], v[150:151], v[152:153]
	v_mov_b32_e32 v152, v30
	v_mov_b32_e32 v153, v26
	v_pk_fma_f32 v[150:151], v[152:153], v[152:153], v[150:151]
	v_mov_b32_e32 v152, v31
	v_mov_b32_e32 v153, v27
	v_pk_fma_f32 v[150:151], v[152:153], v[152:153], v[150:151]
	v_mov_b32_e32 v152, v20
	v_mov_b32_e32 v153, v16
	v_pk_fma_f32 v[152:153], v[152:153], v[152:153], v[154:155]
	v_mov_b32_e32 v154, v22
	v_mov_b32_e32 v155, v18
	v_pk_fma_f32 v[152:153], v[154:155], v[154:155], v[152:153]
	v_mov_b32_e32 v154, v23
	v_mov_b32_e32 v155, v19
	v_pk_fma_f32 v[152:153], v[154:155], v[154:155], v[152:153]
	v_mov_b32_e32 v154, v72
	v_mov_b32_e32 v155, v68
	v_pk_fma_f32 v[154:155], v[154:155], v[154:155], v[156:157]
	v_mov_b32_e32 v156, v74
	v_mov_b32_e32 v157, v70
	v_pk_fma_f32 v[154:155], v[156:157], v[156:157], v[154:155]
	v_mov_b32_e32 v156, v75
	v_mov_b32_e32 v157, v71
	v_pk_fma_f32 v[154:155], v[156:157], v[156:157], v[154:155]
	v_mov_b32_e32 v156, v64
	v_mov_b32_e32 v157, v60
	v_pk_fma_f32 v[156:157], v[156:157], v[156:157], v[190:191]
	v_mov_b32_e32 v190, v66
	v_mov_b32_e32 v191, v62
	v_pk_fma_f32 v[156:157], v[190:191], v[190:191], v[156:157]
	v_mov_b32_e32 v190, v67
	v_mov_b32_e32 v191, v63
	v_pk_fma_f32 v[156:157], v[190:191], v[190:191], v[156:157]
	v_mov_b32_e32 v190, v186
	v_mov_b32_e32 v191, v174
	v_mov_b32_e32 v174, v187
	v_pk_add_f32 v[174:175], v[190:191], v[174:175]
	v_mov_b32_e32 v186, v188
	v_mov_b32_e32 v187, v176
	v_pk_add_f32 v[174:175], v[174:175], v[186:187]
	v_mov_b32_e32 v176, v189
	v_pk_add_f32 v[174:175], v[174:175], v[176:177]
	ds_bpermute_b32 v177, v178, v175
	ds_bpermute_b32 v176, v178, v174
	s_waitcnt lgkmcnt(0)
	v_pk_add_f32 v[174:175], v[174:175], v[176:177]
	ds_bpermute_b32 v177, v179, v175
	ds_bpermute_b32 v176, v179, v174
	s_waitcnt lgkmcnt(0)
	v_pk_add_f32 v[174:175], v[174:175], v[176:177]
	ds_bpermute_b32 v177, v180, v175
	ds_bpermute_b32 v176, v180, v174
	s_waitcnt lgkmcnt(0)
	v_pk_add_f32 v[174:175], v[174:175], v[176:177]
	ds_bpermute_b32 v177, v183, v175
	ds_bpermute_b32 v176, v183, v174
	s_waitcnt lgkmcnt(0)
	v_pk_add_f32 v[174:175], v[174:175], v[176:177]
	ds_bpermute_b32 v177, v184, v175
	ds_bpermute_b32 v176, v184, v174
	s_waitcnt lgkmcnt(0)
	v_pk_add_f32 v[174:175], v[174:175], v[176:177]
	ds_bpermute_b32 v177, v185, v175
	ds_bpermute_b32 v176, v185, v174
	s_waitcnt lgkmcnt(0)
	v_pk_add_f32 v[176:177], v[174:175], v[176:177]
	v_mov_b64_e32 v[174:175], s[14:15]
	v_pk_fma_f32 v[176:177], v[176:177], s[2:3], v[174:175] op_sel_hi:[1,0,0]
	s_nop 0
	v_mul_f32_e32 v145, 0x4b800000, v177
	v_cmp_gt_f32_e64 s[0:1], s3, v177
	v_cmp_gt_f32_e32 vcc, s3, v176
	s_nop 0
	v_cndmask_b32_e64 v145, v177, v145, s[0:1]
	v_rsq_f32_e32 v145, v145
	s_nop 0
	v_mul_f32_e32 v177, 0x45800000, v145
	v_cndmask_b32_e64 v186, v145, v177, s[0:1]
	v_pk_mul_f32 v[140:141], v[140:141], v[186:187] op_sel_hi:[1,0]
	v_pk_mul_f32 v[142:143], v[142:143], v[186:187] op_sel_hi:[1,0]
	v_pk_mul_f32 v[140:141], v[12:13], v[140:141]
	v_pk_mul_f32 v[142:143], v[14:15], v[142:143]
	v_pk_mul_f32 v[128:129], v[128:129], v[186:187] op_sel_hi:[1,0]
	v_pk_mul_f32 v[130:131], v[130:131], v[186:187] op_sel_hi:[1,0]
	v_cvt_pk_bf16_f32 v140, v140, v141
	v_cvt_pk_bf16_f32 v141, v142, v143
	v_add_co_u32_e64 v142, s[0:1], s10, v146
	v_pk_mul_f32 v[128:129], v[0:1], v[128:129]
	v_pk_mul_f32 v[130:131], v[2:3], v[130:131]
	v_addc_co_u32_e64 v143, s[0:1], -1, v147, s[0:1]
	v_cvt_pk_bf16_f32 v128, v128, v129
	v_cvt_pk_bf16_f32 v129, v130, v131
	global_store_dwordx2 v[142:143], v[128:129], off offset:-2048
	v_mul_f32_e32 v128, 0x4b800000, v176
	v_cndmask_b32_e32 v128, v176, v128, vcc
	v_rsq_f32_e32 v128, v128
	v_pk_mul_f32 v[136:137], v[136:137], v[186:187] op_sel_hi:[1,0]
	v_pk_mul_f32 v[138:139], v[138:139], v[186:187] op_sel_hi:[1,0]
	v_pk_mul_f32 v[132:133], v[132:133], v[186:187] op_sel_hi:[1,0]
	v_mul_f32_e32 v129, 0x45800000, v128
	v_cndmask_b32_e32 v128, v128, v129, vcc
	v_pk_mul_f32 v[112:113], v[112:113], v[128:129] op_sel_hi:[1,0]
	v_pk_mul_f32 v[114:115], v[114:115], v[128:129] op_sel_hi:[1,0]
	v_pk_mul_f32 v[112:113], v[0:1], v[112:113]
	v_pk_mul_f32 v[114:115], v[2:3], v[114:115]
	v_pk_mul_f32 v[116:117], v[116:117], v[128:129] op_sel_hi:[1,0]
	v_pk_mul_f32 v[118:119], v[118:119], v[128:129] op_sel_hi:[1,0]
	v_cvt_pk_bf16_f32 v112, v112, v113
	v_cvt_pk_bf16_f32 v113, v114, v115
	v_add_co_u32_e32 v114, vcc, s11, v146
	v_pk_mul_f32 v[116:117], v[4:5], v[116:117]
	v_pk_mul_f32 v[118:119], v[6:7], v[118:119]
	v_addc_co_u32_e32 v115, vcc, -1, v147, vcc
	v_cvt_pk_bf16_f32 v116, v116, v117
	v_cvt_pk_bf16_f32 v117, v118, v119
	global_store_dwordx2 v[114:115], v[112:113], off offset:-4096
	v_mov_b32_e32 v112, v170
	v_mov_b32_e32 v113, v166
	v_mov_b32_e32 v166, v171
	global_store_dwordx2 v[142:143], v[116:117], off offset:-512
	v_pk_add_f32 v[112:113], v[112:113], v[166:167]
	v_mov_b32_e32 v116, v172
	v_mov_b32_e32 v117, v168
	v_pk_add_f32 v[112:113], v[112:113], v[116:117]
	v_mov_b32_e32 v168, v173
	v_pk_add_f32 v[112:113], v[112:113], v[168:169]
	ds_bpermute_b32 v117, v178, v113
	ds_bpermute_b32 v116, v178, v112
	v_pk_mul_f32 v[134:135], v[134:135], v[186:187] op_sel_hi:[1,0]
	v_pk_mul_f32 v[124:125], v[124:125], v[128:129] op_sel_hi:[1,0]
	v_pk_mul_f32 v[126:127], v[126:127], v[128:129] op_sel_hi:[1,0]
	v_pk_mul_f32 v[120:121], v[120:121], v[128:129] op_sel_hi:[1,0]
	s_waitcnt lgkmcnt(0)
; template <bool TO_BF16>
; DI void rms_rows(const int tid, const float* src, const float* gam, bf16_t* dst, float* fdst, int G, int c) {
;     ...
;         for (int o = 32; o > 0; o >>= 1)
; #pragma unroll
;             for (int q = 0; q < NR; ++q) s[q] += __shfl_xor(s[q], o);
; #pragma unroll
;         for (int q = 0; q < NR; ++q) { const float sc = rsqrtf(s[q] * (1.f / 1024.f) + 1e-6f);
; #pragma unroll
;             for (int k = 0; k < 4; ++k) {
;                 if (TO_BF16) { u32x2 o; o.x = pk2(v[q][k][0] * sc * g4[k][0], v[q][k][1] * sc * g4[k][1]); o.y = pk2(v[q][k][2] * sc * g4[k][2], v[q][k][3] * sc * g4[k][3]);
;                     *(u32x2*)(dst + (size_t)(r + q) * 1024 + k * 256 + lane * 4) = o; }
;                 else *(f32x4*)(fdst + (size_t)(r + q) * 1024 + k * 256 + lane * 4) = v[q][k] * sc * g4[k]; } }
	v_pk_add_f32 v[112:113], v[112:113], v[116:117]
	ds_bpermute_b32 v117, v179, v113
	ds_bpermute_b32 v116, v179, v112
	v_pk_mul_f32 v[122:123], v[122:123], v[128:129] op_sel_hi:[1,0]
	v_pk_mul_f32 v[136:137], v[8:9], v[136:137]
	v_pk_mul_f32 v[138:139], v[10:11], v[138:139]
	v_pk_mul_f32 v[132:133], v[4:5], v[132:133]
	s_waitcnt lgkmcnt(0)
	v_pk_add_f32 v[112:113], v[112:113], v[116:117]
	ds_bpermute_b32 v117, v180, v113
	ds_bpermute_b32 v116, v180, v112
	v_pk_mul_f32 v[134:135], v[6:7], v[134:135]
	v_pk_mul_f32 v[124:125], v[12:13], v[124:125]
	v_pk_mul_f32 v[126:127], v[14:15], v[126:127]
	v_pk_mul_f32 v[120:121], v[8:9], v[120:121]
	s_waitcnt lgkmcnt(0)
	v_pk_add_f32 v[112:113], v[112:113], v[116:117]
	ds_bpermute_b32 v117, v183, v113
	ds_bpermute_b32 v116, v183, v112
	v_pk_mul_f32 v[122:123], v[10:11], v[122:123]
	v_cvt_pk_bf16_f32 v136, v136, v137
	v_cvt_pk_bf16_f32 v137, v138, v139
	v_cvt_pk_bf16_f32 v132, v132, v133
	s_waitcnt lgkmcnt(0)
	v_pk_add_f32 v[112:113], v[112:113], v[116:117]
	ds_bpermute_b32 v117, v184, v113
	ds_bpermute_b32 v116, v184, v112
	v_cvt_pk_bf16_f32 v133, v134, v135
	v_cvt_pk_bf16_f32 v124, v124, v125
	v_cvt_pk_bf16_f32 v125, v126, v127
	v_cvt_pk_bf16_f32 v120, v120, v121
	s_waitcnt lgkmcnt(0)
	v_pk_add_f32 v[112:113], v[112:113], v[116:117]
	ds_bpermute_b32 v117, v185, v113
	ds_bpermute_b32 v116, v185, v112
	v_cvt_pk_bf16_f32 v121, v122, v123
	global_store_dwordx2 v[142:143], v[140:141], off offset:-3584
	global_store_dwordx2 v[142:143], v[136:137], off offset:-3072
	global_store_dwordx2 v[142:143], v[132:133], off offset:-2560
	s_waitcnt lgkmcnt(0)
	v_pk_add_f32 v[112:113], v[112:113], v[116:117]
	global_store_dwordx2 v[142:143], v[124:125], off offset:-1536
	v_pk_fma_f32 v[112:113], v[112:113], s[2:3], v[174:175] op_sel_hi:[1,0,0]
	global_store_dwordx2 v[142:143], v[120:121], off offset:-1024
	v_mul_f32_e32 v116, 0x4b800000, v113
	v_cmp_gt_f32_e64 s[0:1], s3, v113
	v_cmp_gt_f32_e32 vcc, s3, v112
	s_nop 0
	v_cndmask_b32_e64 v113, v113, v116, s[0:1]
	v_rsq_f32_e32 v113, v113
	s_nop 0
	v_mul_f32_e32 v116, 0x45800000, v113
	v_cndmask_b32_e64 v116, v113, v116, s[0:1]
	v_pk_mul_f32 v[96:97], v[96:97], v[116:117] op_sel_hi:[1,0]
	v_pk_mul_f32 v[98:99], v[98:99], v[116:117] op_sel_hi:[1,0]
	v_pk_mul_f32 v[96:97], v[0:1], v[96:97]
	v_pk_mul_f32 v[98:99], v[2:3], v[98:99]
	v_cvt_pk_bf16_f32 v96, v96, v97
	v_cvt_pk_bf16_f32 v97, v98, v99
	global_store_dwordx2 v[114:115], v[96:97], off offset:-2048
	v_mul_f32_e32 v96, 0x4b800000, v112
	v_cndmask_b32_e32 v96, v112, v96, vcc
	v_rsq_f32_e32 v96, v96
	v_pk_mul_f32 v[108:109], v[108:109], v[116:117] op_sel_hi:[1,0]
	v_pk_mul_f32 v[110:111], v[110:111], v[116:117] op_sel_hi:[1,0]
	v_pk_mul_f32 v[104:105], v[104:105], v[116:117] op_sel_hi:[1,0]
	v_mul_f32_e32 v97, 0x45800000, v96
	v_cndmask_b32_e32 v96, v96, v97, vcc
	v_pk_mul_f32 v[80:81], v[80:81], v[96:97] op_sel_hi:[1,0]
	v_pk_mul_f32 v[82:83], v[82:83], v[96:97] op_sel_hi:[1,0]
	v_pk_mul_f32 v[80:81], v[0:1], v[80:81]
	v_pk_mul_f32 v[82:83], v[2:3], v[82:83]
	v_cvt_pk_bf16_f32 v80, v80, v81
	v_cvt_pk_bf16_f32 v81, v82, v83
	global_store_dwordx2 v[114:115], v[80:81], off
	v_mov_b32_e32 v80, v162
	v_mov_b32_e32 v81, v158
	v_mov_b32_e32 v158, v163
	v_pk_add_f32 v[80:81], v[80:81], v[158:159]
	v_mov_b32_e32 v82, v164
	v_mov_b32_e32 v83, v160
	v_pk_add_f32 v[80:81], v[80:81], v[82:83]
	v_mov_b32_e32 v160, v165
	v_pk_add_f32 v[80:81], v[80:81], v[160:161]
	ds_bpermute_b32 v83, v178, v81
	ds_bpermute_b32 v82, v178, v80
	v_pk_mul_f32 v[106:107], v[106:107], v[116:117] op_sel_hi:[1,0]
	v_pk_mul_f32 v[100:101], v[100:101], v[116:117] op_sel_hi:[1,0]
	v_pk_mul_f32 v[102:103], v[102:103], v[116:117] op_sel_hi:[1,0]
	v_pk_mul_f32 v[92:93], v[92:93], v[96:97] op_sel_hi:[1,0]
	s_waitcnt lgkmcnt(0)
	v_pk_add_f32 v[80:81], v[80:81], v[82:83]
	ds_bpermute_b32 v83, v179, v81
	ds_bpermute_b32 v82, v179, v80
	v_pk_mul_f32 v[94:95], v[94:95], v[96:97] op_sel_hi:[1,0]
	v_pk_mul_f32 v[88:89], v[88:89], v[96:97] op_sel_hi:[1,0]
	v_pk_mul_f32 v[90:91], v[90:91], v[96:97] op_sel_hi:[1,0]
	v_pk_mul_f32 v[84:85], v[84:85], v[96:97] op_sel_hi:[1,0]
	s_waitcnt lgkmcnt(0)
	v_pk_add_f32 v[80:81], v[80:81], v[82:83]
	ds_bpermute_b32 v83, v180, v81
	ds_bpermute_b32 v82, v180, v80
	v_pk_mul_f32 v[86:87], v[86:87], v[96:97] op_sel_hi:[1,0]
	v_pk_mul_f32 v[108:109], v[12:13], v[108:109]
	v_pk_mul_f32 v[110:111], v[14:15], v[110:111]
	v_pk_mul_f32 v[104:105], v[8:9], v[104:105]
	s_waitcnt lgkmcnt(0)
	v_pk_add_f32 v[80:81], v[80:81], v[82:83]
	ds_bpermute_b32 v83, v183, v81
	ds_bpermute_b32 v82, v183, v80
	v_pk_mul_f32 v[106:107], v[10:11], v[106:107]
	v_pk_mul_f32 v[100:101], v[4:5], v[100:101]
	v_pk_mul_f32 v[102:103], v[6:7], v[102:103]
	v_pk_mul_f32 v[92:93], v[12:13], v[92:93]
	s_waitcnt lgkmcnt(0)
	v_pk_add_f32 v[80:81], v[80:81], v[82:83]
	ds_bpermute_b32 v83, v184, v81
	ds_bpermute_b32 v82, v184, v80
	v_pk_mul_f32 v[94:95], v[14:15], v[94:95]
	v_pk_mul_f32 v[88:89], v[8:9], v[88:89]
	v_pk_mul_f32 v[90:91], v[10:11], v[90:91]
	v_pk_mul_f32 v[84:85], v[4:5], v[84:85]
	s_waitcnt lgkmcnt(0)
	v_pk_add_f32 v[80:81], v[80:81], v[82:83]
	ds_bpermute_b32 v83, v185, v81
	ds_bpermute_b32 v82, v185, v80
	v_pk_mul_f32 v[86:87], v[6:7], v[86:87]
	v_cvt_pk_bf16_f32 v108, v108, v109
	v_cvt_pk_bf16_f32 v109, v110, v111
	v_cvt_pk_bf16_f32 v104, v104, v105
	s_waitcnt lgkmcnt(0)
; template <bool TO_BF16>
; DI void rms_rows(const int tid, const float* src, const float* gam, bf16_t* dst, float* fdst, int G, int c) {
;     ...
;         for (int o = 32; o > 0; o >>= 1)
; #pragma unroll
;             for (int q = 0; q < NR; ++q) s[q] += __shfl_xor(s[q], o);
; #pragma unroll
;         for (int q = 0; q < NR; ++q) { const float sc = rsqrtf(s[q] * (1.f / 1024.f) + 1e-6f);
; #pragma unroll
;             for (int k = 0; k < 4; ++k) {
;                 if (TO_BF16) { u32x2 o; o.x = pk2(v[q][k][0] * sc * g4[k][0], v[q][k][1] * sc * g4[k][1]); o.y = pk2(v[q][k][2] * sc * g4[k][2], v[q][k][3] * sc * g4[k][3]);
;                     *(u32x2*)(dst + (size_t)(r + q) * 1024 + k * 256 + lane * 4) = o; }
;                 else *(f32x4*)(fdst + (size_t)(r + q) * 1024 + k * 256 + lane * 4) = v[q][k] * sc * g4[k]; } }
	v_pk_add_f32 v[80:81], v[80:81], v[82:83]
	v_cvt_pk_bf16_f32 v105, v106, v107
	v_pk_fma_f32 v[80:81], v[80:81], s[2:3], v[174:175] op_sel_hi:[1,0,0]
	v_cvt_pk_bf16_f32 v100, v100, v101
	v_mul_f32_e32 v82, 0x4b800000, v81
	v_cmp_gt_f32_e64 s[0:1], s3, v81
	v_cmp_gt_f32_e32 vcc, s3, v80
	v_cvt_pk_bf16_f32 v101, v102, v103
	v_cndmask_b32_e64 v81, v81, v82, s[0:1]
	v_rsq_f32_e32 v81, v81
	v_cvt_pk_bf16_f32 v92, v92, v93
	v_cvt_pk_bf16_f32 v93, v94, v95
	v_cvt_pk_bf16_f32 v88, v88, v89
	v_mul_f32_e32 v82, 0x45800000, v81
	v_cndmask_b32_e64 v82, v81, v82, s[0:1]
	v_pk_mul_f32 v[76:77], v[76:77], v[82:83] op_sel_hi:[1,0]
	v_pk_mul_f32 v[78:79], v[78:79], v[82:83] op_sel_hi:[1,0]
	v_pk_mul_f32 v[76:77], v[12:13], v[76:77]
	v_pk_mul_f32 v[78:79], v[14:15], v[78:79]
	v_pk_mul_f32 v[48:49], v[48:49], v[82:83] op_sel_hi:[1,0]
	v_pk_mul_f32 v[50:51], v[50:51], v[82:83] op_sel_hi:[1,0]
	v_cvt_pk_bf16_f32 v76, v76, v77
	v_cvt_pk_bf16_f32 v77, v78, v79
	v_add_co_u32_e64 v78, s[0:1], s12, v146
	v_pk_mul_f32 v[48:49], v[0:1], v[48:49]
	v_pk_mul_f32 v[50:51], v[2:3], v[50:51]
	v_addc_co_u32_e64 v79, s[0:1], -1, v147, s[0:1]
	v_cvt_pk_bf16_f32 v48, v48, v49
	v_cvt_pk_bf16_f32 v49, v50, v51
	global_store_dwordx2 v[78:79], v[48:49], off offset:-2048
	v_mul_f32_e32 v48, 0x4b800000, v80
	v_cndmask_b32_e32 v48, v80, v48, vcc
	v_rsq_f32_e32 v48, v48
	v_pk_mul_f32 v[56:57], v[56:57], v[82:83] op_sel_hi:[1,0]
	v_pk_mul_f32 v[58:59], v[58:59], v[82:83] op_sel_hi:[1,0]
	v_pk_mul_f32 v[52:53], v[52:53], v[82:83] op_sel_hi:[1,0]
	v_mul_f32_e32 v49, 0x45800000, v48
	v_cndmask_b32_e32 v48, v48, v49, vcc
	v_pk_mul_f32 v[32:33], v[32:33], v[48:49] op_sel_hi:[1,0]
	v_pk_mul_f32 v[34:35], v[34:35], v[48:49] op_sel_hi:[1,0]
	v_pk_mul_f32 v[32:33], v[0:1], v[32:33]
	v_pk_mul_f32 v[34:35], v[2:3], v[34:35]
	v_cvt_pk_bf16_f32 v32, v32, v33
	v_cvt_pk_bf16_f32 v33, v34, v35
	global_store_dwordx2 v[146:147], v[32:33], off offset:-4096
	v_mov_b32_e32 v32, v154
	v_mov_b32_e32 v33, v150
	v_mov_b32_e32 v150, v155
	v_pk_add_f32 v[32:33], v[32:33], v[150:151]
	v_mov_b32_e32 v34, v156
	v_mov_b32_e32 v35, v152
	v_pk_add_f32 v[32:33], v[32:33], v[34:35]
	v_mov_b32_e32 v152, v157
	v_pk_add_f32 v[32:33], v[32:33], v[152:153]
	ds_bpermute_b32 v35, v178, v33
	ds_bpermute_b32 v34, v178, v32
	v_pk_mul_f32 v[54:55], v[54:55], v[82:83] op_sel_hi:[1,0]
	v_pk_mul_f32 v[44:45], v[44:45], v[48:49] op_sel_hi:[1,0]
	v_pk_mul_f32 v[46:47], v[46:47], v[48:49] op_sel_hi:[1,0]
	v_pk_mul_f32 v[40:41], v[40:41], v[48:49] op_sel_hi:[1,0]
	s_waitcnt lgkmcnt(0)
	v_pk_add_f32 v[32:33], v[32:33], v[34:35]
	ds_bpermute_b32 v35, v179, v33
	ds_bpermute_b32 v34, v179, v32
	v_pk_mul_f32 v[42:43], v[42:43], v[48:49] op_sel_hi:[1,0]
	v_pk_mul_f32 v[36:37], v[36:37], v[48:49] op_sel_hi:[1,0]
	v_pk_mul_f32 v[38:39], v[38:39], v[48:49] op_sel_hi:[1,0]
	v_pk_mul_f32 v[56:57], v[8:9], v[56:57]
	s_waitcnt lgkmcnt(0)
	v_pk_add_f32 v[32:33], v[32:33], v[34:35]
	ds_bpermute_b32 v35, v180, v33
	ds_bpermute_b32 v34, v180, v32
	v_pk_mul_f32 v[58:59], v[10:11], v[58:59]
	v_pk_mul_f32 v[52:53], v[4:5], v[52:53]
	v_pk_mul_f32 v[54:55], v[6:7], v[54:55]
	v_pk_mul_f32 v[44:45], v[12:13], v[44:45]
	s_waitcnt lgkmcnt(0)
	v_pk_add_f32 v[32:33], v[32:33], v[34:35]
	ds_bpermute_b32 v35, v183, v33
	ds_bpermute_b32 v34, v183, v32
	v_pk_mul_f32 v[46:47], v[14:15], v[46:47]
	v_pk_mul_f32 v[40:41], v[8:9], v[40:41]
	v_pk_mul_f32 v[42:43], v[10:11], v[42:43]
	v_pk_mul_f32 v[36:37], v[4:5], v[36:37]
	s_waitcnt lgkmcnt(0)
	v_pk_add_f32 v[32:33], v[32:33], v[34:35]
	ds_bpermute_b32 v35, v184, v33
	ds_bpermute_b32 v34, v184, v32
	v_pk_mul_f32 v[38:39], v[6:7], v[38:39]
	v_cvt_pk_bf16_f32 v89, v90, v91
	v_cvt_pk_bf16_f32 v84, v84, v85
	v_cvt_pk_bf16_f32 v85, v86, v87
	s_waitcnt lgkmcnt(0)
	v_pk_add_f32 v[32:33], v[32:33], v[34:35]
	ds_bpermute_b32 v35, v185, v33
	ds_bpermute_b32 v34, v185, v32
	v_cvt_pk_bf16_f32 v56, v56, v57
	v_cvt_pk_bf16_f32 v57, v58, v59
	v_cvt_pk_bf16_f32 v52, v52, v53
	v_cvt_pk_bf16_f32 v53, v54, v55
	s_waitcnt lgkmcnt(0)
; template <bool TO_BF16>
; DI void rms_rows(const int tid, const float* src, const float* gam, bf16_t* dst, float* fdst, int G, int c) {
;     ...
;     for (int r = (c * 8 + wave) * NR; r < MTOK; r += G * 8 * NR) {
;         f32x4 v[NR][4]; float s[NR];
; #pragma unroll
;         for (int q = 0; q < NR; ++q)
; #pragma unroll
;             for (int k = 0; k < 4; ++k) v[q][k] = *(const f32x4*)(src + (size_t)(r + q) * 1024 + k * 256 + lane * 4);
; #pragma unroll
;         for (int q = 0; q < NR; ++q) { s[q] = 0.f;
; #pragma unroll
;             for (int k = 0; k < 4; ++k) s[q] += v[q][k][0] * v[q][k][0] + v[q][k][1] * v[q][k][1] + v[q][k][2] * v[q][k][2] + v[q][k][3] * v[q][k][3]; }
; #pragma unroll
;         for (int o = 32; o > 0; o >>= 1)
; #pragma unroll
;             for (int q = 0; q < NR; ++q) s[q] += __shfl_xor(s[q], o);
; #pragma unroll
;         for (int q = 0; q < NR; ++q) { const float sc = rsqrtf(s[q] * (1.f / 1024.f) + 1e-6f);
; #pragma unroll
;             for (int k = 0; k < 4; ++k) {
;                 if (TO_BF16) { u32x2 o; o.x = pk2(v[q][k][0] * sc * g4[k][0], v[q][k][1] * sc * g4[k][1]); o.y = pk2(v[q][k][2] * sc * g4[k][2], v[q][k][3] * sc * g4[k][3]);
;                     *(u32x2*)(dst + (size_t)(r + q) * 1024 + k * 256 + lane * 4) = o; }
;                 else *(f32x4*)(fdst + (size_t)(r + q) * 1024 + k * 256 + lane * 4) = v[q][k] * sc * g4[k]; } }
	v_pk_add_f32 v[32:33], v[32:33], v[34:35]
	v_cvt_pk_bf16_f32 v44, v44, v45
	v_pk_fma_f32 v[32:33], v[32:33], s[2:3], v[174:175] op_sel_hi:[1,0,0]
	v_cvt_pk_bf16_f32 v45, v46, v47
	v_mul_f32_e32 v34, 0x4b800000, v33
	v_cmp_gt_f32_e64 s[0:1], s3, v33
	v_cmp_gt_f32_e32 vcc, s3, v32
	v_cvt_pk_bf16_f32 v40, v40, v41
	v_cndmask_b32_e64 v33, v33, v34, s[0:1]
	v_rsq_f32_e32 v33, v33
	v_cvt_pk_bf16_f32 v41, v42, v43
	v_cvt_pk_bf16_f32 v36, v36, v37
	v_cvt_pk_bf16_f32 v37, v38, v39
	v_mul_f32_e32 v34, 0x45800000, v33
	v_cndmask_b32_e64 v34, v33, v34, s[0:1]
	v_pk_mul_f32 v[16:17], v[16:17], v[34:35] op_sel_hi:[1,0]
	v_pk_mul_f32 v[18:19], v[18:19], v[34:35] op_sel_hi:[1,0]
	v_pk_mul_f32 v[16:17], v[0:1], v[16:17]
	v_pk_mul_f32 v[18:19], v[2:3], v[18:19]
	v_cvt_pk_bf16_f32 v16, v16, v17
	v_cvt_pk_bf16_f32 v17, v18, v19
	global_store_dwordx2 v[146:147], v[16:17], off offset:-2048
	v_mul_f32_e32 v16, 0x4b800000, v32
	v_cndmask_b32_e32 v16, v32, v16, vcc
	v_rsq_f32_e32 v16, v16
	v_pk_mul_f32 v[20:21], v[20:21], v[34:35] op_sel_hi:[1,0]
	v_pk_mul_f32 v[22:23], v[22:23], v[34:35] op_sel_hi:[1,0]
	v_pk_mul_f32 v[20:21], v[4:5], v[20:21]
	v_pk_mul_f32 v[22:23], v[6:7], v[22:23]
	v_mul_f32_e32 v17, 0x45800000, v16
	v_cvt_pk_bf16_f32 v20, v20, v21
	v_cvt_pk_bf16_f32 v21, v22, v23
	v_cndmask_b32_e32 v16, v16, v17, vcc
	global_store_dwordx2 v[146:147], v[20:21], off offset:-2560
	v_pk_mul_f32 v[18:19], v[72:73], v[16:17] op_sel_hi:[1,0]
	v_pk_mul_f32 v[20:21], v[74:75], v[16:17] op_sel_hi:[1,0]
	v_pk_mul_f32 v[18:19], v[12:13], v[18:19]
	v_pk_mul_f32 v[20:21], v[14:15], v[20:21]
	v_cvt_pk_bf16_f32 v18, v18, v19
	v_cvt_pk_bf16_f32 v19, v20, v21
	global_store_dwordx2 v[146:147], v[18:19], off offset:-1536
	v_pk_mul_f32 v[18:19], v[68:69], v[16:17] op_sel_hi:[1,0]
	v_pk_mul_f32 v[20:21], v[70:71], v[16:17] op_sel_hi:[1,0]
	v_pk_mul_f32 v[18:19], v[8:9], v[18:19]
	v_pk_mul_f32 v[20:21], v[10:11], v[20:21]
	v_cvt_pk_bf16_f32 v18, v18, v19
	v_cvt_pk_bf16_f32 v19, v20, v21
	global_store_dwordx2 v[146:147], v[18:19], off offset:-1024
	v_pk_mul_f32 v[18:19], v[64:65], v[16:17] op_sel_hi:[1,0]
	v_pk_mul_f32 v[20:21], v[66:67], v[16:17] op_sel_hi:[1,0]
	v_pk_mul_f32 v[18:19], v[4:5], v[18:19]
	v_pk_mul_f32 v[20:21], v[6:7], v[20:21]
	v_cvt_pk_bf16_f32 v18, v18, v19
	v_cvt_pk_bf16_f32 v19, v20, v21
	v_pk_mul_f32 v[28:29], v[28:29], v[34:35] op_sel_hi:[1,0]
	v_pk_mul_f32 v[30:31], v[30:31], v[34:35] op_sel_hi:[1,0]
	v_pk_mul_f32 v[24:25], v[24:25], v[34:35] op_sel_hi:[1,0]
	v_pk_mul_f32 v[26:27], v[26:27], v[34:35] op_sel_hi:[1,0]
	global_store_dwordx2 v[146:147], v[18:19], off offset:-512
	v_pk_mul_f32 v[18:19], v[60:61], v[16:17] op_sel_hi:[1,0]
	v_pk_mul_f32 v[16:17], v[62:63], v[16:17] op_sel_hi:[1,0]
	v_pk_mul_f32 v[28:29], v[12:13], v[28:29]
	v_pk_mul_f32 v[30:31], v[14:15], v[30:31]
	v_pk_mul_f32 v[24:25], v[8:9], v[24:25]
	v_pk_mul_f32 v[26:27], v[10:11], v[26:27]
	v_pk_mul_f32 v[18:19], v[0:1], v[18:19]
	v_pk_mul_f32 v[16:17], v[2:3], v[16:17]
	v_cvt_pk_bf16_f32 v28, v28, v29
	v_cvt_pk_bf16_f32 v29, v30, v31
	v_cvt_pk_bf16_f32 v24, v24, v25
	v_cvt_pk_bf16_f32 v25, v26, v27
	v_cvt_pk_bf16_f32 v18, v18, v19
	v_cvt_pk_bf16_f32 v19, v16, v17
	v_cmp_lt_i32_e32 vcc, s70, v144
	global_store_dwordx2 v[146:147], v[28:29], off offset:-3584
	global_store_dwordx2 v[146:147], v[24:25], off offset:-3072
	global_store_dwordx2 v[146:147], v[18:19], off
	v_bfe_u32 v146, v144, 11, 3
	v_lshrrev_b32_e32 v147, 14, v144
	v_sub_u32_e32 v147, 3, v147
	v_lshlrev_b32_e32 v147, 11, v147
	v_lshl_or_b32 v146, v146, 13, v147
	v_and_b32_e32 v147, 0x7ff, v144
	v_or_b32_e32 v146, v146, v147
	v_lshlrev_b32_e32 v146, 11, v146
	v_and_b32_e32 v147, 63, v182
	v_lshl_or_b32 v146, v147, 3, v146
	v_mov_b32_e32 v147, 0
	v_lshl_add_u64 v[146:147], s[100:101], 0, v[146:147]
	s_or_b64 s[6:7], vcc, s[6:7]
	global_store_dwordx2 v[114:115], v[108:109], off offset:-3584
	global_store_dwordx2 v[114:115], v[104:105], off offset:-3072
	global_store_dwordx2 v[114:115], v[100:101], off offset:-2560
	global_store_dwordx2 v[114:115], v[92:93], off offset:-1536
	global_store_dwordx2 v[114:115], v[88:89], off offset:-1024
	global_store_dwordx2 v[114:115], v[84:85], off offset:-512
	global_store_dwordx2 v[78:79], v[76:77], off offset:-3584
	global_store_dwordx2 v[78:79], v[56:57], off offset:-3072
	global_store_dwordx2 v[78:79], v[52:53], off offset:-2560
	global_store_dwordx2 v[78:79], v[44:45], off offset:-1536
	global_store_dwordx2 v[78:79], v[40:41], off offset:-1024
	global_store_dwordx2 v[78:79], v[36:37], off offset:-512
	s_andn2_b64 exec, exec, s[6:7]
	s_cbranch_execnz .LBB0_394
